# v37 + NSA softmax p-sum: 25 'x + 0' adds on v_exp_f32 results folded away (exact)
# baseline (speedup 1.0000x reference)
; template <int MODE>
; __device__ __forceinline__ void nsa_compute(int cur, int buf, int t, int hl, u64 mymask, const bf16x8 (&Qf)[2][2], f32x4 (&O)[4][2], float (&m)[2], float (&l)[2],
;                                             const float (&inv)[2], float* impw, char* lds) {
;     ...
;         const float mxa = fmaxf(fmaxf(sv[0][0], sv[0][1]), sv[0][2]), mxb = fmaxf(fmaxf(sv[0][3], sv[1][0]), sv[1][1]);
;         float mx = fmaxf(fmaxf(fmaxf(sv[1][2], sv[1][3]), mxa), mxb);
;         if (MODE == 2) mx = selok ? mx : -__builtin_inff();
;         if (__any(mx > m[r] + 8.0f)) {
;           mx = fmaxf(mx, __shfl_xor(mx, 16)); mx = fmaxf(mx, __shfl_xor(mx, 32));
;           const float mn = fmaxf(m[r], mx), al = __builtin_amdgcn_exp2f(m[r] - mn);
;           m[r] = mn; l[r] *= al;
;           if (MODE != 0) {
; #pragma unroll
;             for (int df = 0; df < 4; ++df) O[df][r] *= al;
;           }
;         }
;         const float me = (MODE == 2) ? (selok ? m[r] : __builtin_inff()) : m[r];
;         float ps = 0.f;
; #pragma unroll
;         for (int kk = 0; kk < 2; ++kk)
; #pragma unroll
;           for (int e = 0; e < 4; ++e) { pv[kk][e] = __builtin_amdgcn_exp2f(sv[kk][e] - me); ps += pv[kk][e]; }
;         l[r] += ps;
.LBB0_214:
	v_sub_f32_e32 v83, v95, v82
	v_exp_f32_e32 v83, v83
	v_sub_f32_e32 v95, v97, v82
	v_exp_f32_e32 v95, v95
	v_sub_f32_e32 v97, v99, v82
	v_exp_f32_e32 v97, v97
	v_sub_f32_e32 v99, v101, v82
	v_exp_f32_e32 v99, v99
	v_add_f32_e32 v83, v95, v83
	v_sub_f32_e32 v95, v102, v82
	v_add_f32_e32 v83, v97, v83
	v_exp_f32_e32 v95, v95
	v_sub_f32_e32 v97, v103, v82
	v_add_f32_e32 v83, v99, v83
	v_exp_f32_e32 v97, v97
	v_sub_f32_e32 v99, v104, v82
	v_exp_f32_e32 v99, v99
	v_add_f32_e32 v83, v95, v83
	v_add_f32_e32 v83, v97, v83
	v_sub_f32_e32 v82, v105, v82
	v_add_f32_e32 v83, v99, v83
	ds_read_b32 v101, v90 offset:50432
	ds_read_b32 v99, v91 offset:50432
	ds_read_b32 v97, v92 offset:50432
	ds_read_b32 v95, v93 offset:50432
	ds_read_b32 v93, v94 offset:50432
	ds_read_b32 v92, v96 offset:50432
	ds_read_b32 v91, v98 offset:50432
	ds_read_b32 v90, v100 offset:50432
	v_exp_f32_e32 v82, v82
	s_waitcnt lgkmcnt(7)
	v_fmac_f32_e32 v101, 0x3e38aa3b, v76
	s_waitcnt lgkmcnt(6)
	v_fmac_f32_e32 v99, 0x3e38aa3b, v77
	s_waitcnt lgkmcnt(5)
	v_fmac_f32_e32 v97, 0x3e38aa3b, v78
	s_waitcnt lgkmcnt(4)
	v_fmac_f32_e32 v95, 0x3e38aa3b, v79
	s_waitcnt lgkmcnt(3)
	v_fmac_f32_e32 v93, 0x3e38aa3b, v72
	s_waitcnt lgkmcnt(2)
	v_fmac_f32_e32 v92, 0x3e38aa3b, v73
	s_waitcnt lgkmcnt(1)
	v_fmac_f32_e32 v91, 0x3e38aa3b, v74
	s_waitcnt lgkmcnt(0)
	v_fmac_f32_e32 v90, 0x3e38aa3b, v75
	v_max3_f32 v72, v101, v99, v97
	v_max3_f32 v73, v95, v93, v92
	v_max_f32_e32 v74, v91, v90
	v_add_f32_e32 v82, v82, v83
	v_max3_f32 v72, v74, v72, v73
	v_add_f32_e32 v73, 0x41000000, v85
	v_add_f32_e32 v80, v80, v82
	v_cmp_gt_f32_e32 vcc, v72, v73
	s_cbranch_vccz .LBB0_264
	v_cmp_lt_i32_e32 vcc, v220, v218
	s_nop 1
	v_cndmask_b32_e32 v73, v212, v220, vcc
	v_lshlrev_b32_e32 v73, 2, v73
	ds_bpermute_b32 v73, v73, v72
	v_cmp_lt_i32_e32 vcc, v219, v218
	v_max_f32_e32 v72, v72, v72
	s_waitcnt lgkmcnt(0)
	v_max_f32_e32 v73, v73, v73
	v_cndmask_b32_e32 v74, v212, v219, vcc
	v_max_f32_e32 v72, v72, v73
	v_lshlrev_b32_e32 v73, 2, v74
	ds_bpermute_b32 v73, v73, v72
	s_waitcnt lgkmcnt(0)
	v_max3_f32 v73, v85, v72, v73
	v_sub_f32_e32 v72, v85, v73
	v_exp_f32_e32 v74, v72
	v_mov_b32_e32 v72, v84
	v_mov_b64_e32 v[82:83], v[72:73]
	v_mul_f32_e32 v81, v81, v74
	s_cbranch_execnz .LBB0_217

; template <int MODE>
; __device__ __forceinline__ void nsa_compute(int cur, int buf, int t, int hl, u64 mymask, const bf16x8 (&Qf)[2][2], f32x4 (&O)[4][2], float (&m)[2], float (&l)[2],
;                                             const float (&inv)[2], float* impw, char* lds) {
;     ...
; #pragma unroll
;     for (int ks = 0; ks < 2; ++ks)
; #pragma unroll
;       for (int kk = 0; kk < 2; ++kk) kfr[ks][kk] = *(const bf16x8*)(kt + (32 * s2 + 16 * kk + fr) * 128 + (((ks * 4 + fq) ^ (fr & 7)) << 4));
;     __builtin_amdgcn_s_setprio(1);
; #pragma unroll
;     for (int ks = 0; ks < 2; ++ks)
; #pragma unroll
;       for (int kk = 0; kk < 2; ++kk)
; #pragma unroll
;         for (int r = 0; r < 2; ++r) S[kk][r] = mfma16(kfr[ks][kk], Qf[r][ks], S[kk][r]);
;     __builtin_amdgcn_s_setprio(0);
;     bf16x8 Pf[2];
;     float g1s[2] = {0.f, 0.f}, p3s[2] = {0.f, 0.f};
; #pragma unroll
;     for (int r = 0; r < 2; ++r) {
;       float sv[2][4];
; #pragma unroll
;       for (int kk = 0; kk < 2; ++kk)
; #pragma unroll
;         for (int e = 0; e < 4; ++e) {
;           const int off = 32 * s2 + 16 * kk + e;
;           int idx;
;           if (MODE <= 1) { idx = base - 16 * off; idx = idx > 0 ? idx : 0; } else idx = base - off;
;           sv[kk][e] = S[kk][r][e] * (0.125f * LOG2E) + tb[r * TS + idx];
;         }
;       float pv[2][4];
;       if (MODE == 1) {
; #pragma unroll
;         for (int kk = 0; kk < 2; ++kk)
; #pragma unroll
;           for (int e = 0; e < 4; ++e) pv[kk][e] = __builtin_amdgcn_exp2f(sv[kk][e] - m[r]) * inv[r];
; #pragma unroll
;         for (int kk = 0; kk < 2; ++kk) { g1s[kk] += pv[kk][0] + pv[kk][1] + pv[kk][2] + 0.5f * pv[kk][3]; p3s[kk] += 0.5f * pv[kk][3]; }
;       } else {
;         const float mxa = fmaxf(fmaxf(sv[0][0], sv[0][1]), sv[0][2]), mxb = fmaxf(fmaxf(sv[0][3], sv[1][0]), sv[1][1]);
;         float mx = fmaxf(fmaxf(fmaxf(sv[1][2], sv[1][3]), mxa), mxb);
;         if (MODE == 2) mx = selok ? mx : -__builtin_inff();
;         if (__any(mx > m[r] + 8.0f)) {
;           mx = fmaxf(mx, __shfl_xor(mx, 16)); mx = fmaxf(mx, __shfl_xor(mx, 32));
;           const float mn = fmaxf(m[r], mx), al = __builtin_amdgcn_exp2f(m[r] - mn);
;           m[r] = mn; l[r] *= al;
;           if (MODE != 0) {
; #pragma unroll
;             for (int df = 0; df < 4; ++df) O[df][r] *= al;
;           }
;         }
.LBB0_217:
	v_sub_f32_e32 v72, v101, v73
	v_exp_f32_e32 v72, v72
	v_sub_f32_e32 v74, v99, v73
	v_exp_f32_e32 v74, v74
	v_add_u32_e32 v76, v88, v87
	v_add_u32_e32 v84, v89, v87
	v_add_f32_e32 v72, v74, v72
	v_sub_f32_e32 v74, v97, v73
	v_exp_f32_e32 v74, v74
	s_nop 0
	v_add_f32_e32 v72, v74, v72
	v_sub_f32_e32 v74, v95, v73
	v_exp_f32_e32 v74, v74
	s_nop 0
	v_add_f32_e32 v72, v74, v72
	v_sub_f32_e32 v74, v93, v73
	v_exp_f32_e32 v74, v74
	s_nop 0
	v_add_f32_e32 v72, v74, v72
	v_sub_f32_e32 v74, v92, v73
	v_exp_f32_e32 v74, v74
	s_nop 0
	v_add_f32_e32 v72, v74, v72
	v_sub_f32_e32 v74, v91, v73
	v_exp_f32_e32 v74, v74
	v_sub_f32_e32 v73, v90, v73
	v_exp_f32_e32 v73, v73
	v_add_f32_e32 v72, v74, v72
	v_add_f32_e32 v72, v73, v72
	v_add_f32_e32 v81, v81, v72
	ds_read_b128 v[72:75], v76 offset:4096
	ds_read_b128 v[76:79], v76 offset:6144
	ds_read_b128 v[88:91], v84 offset:4096
	ds_read_b128 v[92:95], v84 offset:6144
	s_setprio 1
	s_waitcnt lgkmcnt(3)
	v_mfma_f32_16x16x32_bf16 v[96:99], v[72:75], v[0:3], 0
	v_mfma_f32_16x16x32_bf16 v[72:75], v[72:75], v[8:11], 0
	s_waitcnt lgkmcnt(2)
	v_mfma_f32_16x16x32_bf16 v[104:107], v[76:79], v[8:11], 0
	v_mfma_f32_16x16x32_bf16 v[100:103], v[76:79], v[0:3], 0
	s_waitcnt lgkmcnt(1)
	v_mfma_f32_16x16x32_bf16 v[76:79], v[88:91], v[12:15], v[72:75]
	s_waitcnt lgkmcnt(0)
	v_mfma_f32_16x16x32_bf16 v[72:75], v[92:95], v[12:15], v[104:107]
	v_mfma_f32_16x16x32_bf16 v[108:111], v[88:91], v[4:7], v[96:99]
	v_mfma_f32_16x16x32_bf16 v[112:115], v[92:95], v[4:7], v[100:103]
	s_setprio 0
	v_add_u32_e32 v84, 0xfffffe00, v86
	v_max_i32_e32 v84, 0, v84
	v_lshl_add_u32 v88, v84, 2, v181
	v_add_u32_e32 v84, 0xfffffdf0, v86
	v_max_i32_e32 v84, 0, v84
	v_lshl_add_u32 v89, v84, 2, v181
	v_add_u32_e32 v84, 0xfffffde0, v86
	v_max_i32_e32 v84, 0, v84
	v_lshl_add_u32 v90, v84, 2, v181
	v_add_u32_e32 v84, 0xfffffdd0, v86
	v_max_i32_e32 v84, 0, v84
	v_lshl_add_u32 v91, v84, 2, v181
	v_add_u32_e32 v84, 0xfffffd00, v86
	v_max_i32_e32 v84, 0, v84
	v_lshl_add_u32 v92, v84, 2, v181
	v_add_u32_e32 v84, 0xfffffcf0, v86
	v_max_i32_e32 v84, 0, v84
	v_lshl_add_u32 v94, v84, 2, v181
	v_add_u32_e32 v84, 0xfffffce0, v86
	v_max_i32_e32 v84, 0, v84
	v_lshl_add_u32 v96, v84, 2, v181
	v_add_u32_e32 v84, 0xfffffcd0, v86
	v_max_i32_e32 v84, 0, v84
	v_lshl_add_u32 v98, v84, 2, v181
	ds_read_b32 v93, v88 offset:33792
	ds_read_b32 v95, v89 offset:33792
	ds_read_b32 v97, v90 offset:33792
	ds_read_b32 v99, v91 offset:33792
	ds_read_b32 v100, v92 offset:33792
	ds_read_b32 v101, v94 offset:33792
	ds_read_b32 v102, v96 offset:33792
	ds_read_b32 v103, v98 offset:33792
	s_waitcnt lgkmcnt(7)
	v_fmac_f32_e32 v93, 0x3e38aa3b, v108
	s_waitcnt lgkmcnt(6)
	v_fmac_f32_e32 v95, 0x3e38aa3b, v109
	s_waitcnt lgkmcnt(5)
	v_fmac_f32_e32 v97, 0x3e38aa3b, v110
	s_waitcnt lgkmcnt(4)
	v_fmac_f32_e32 v99, 0x3e38aa3b, v111
	s_waitcnt lgkmcnt(3)
	v_fmac_f32_e32 v100, 0x3e38aa3b, v112
	s_waitcnt lgkmcnt(2)
	v_fmac_f32_e32 v101, 0x3e38aa3b, v113
	s_waitcnt lgkmcnt(1)
	v_fmac_f32_e32 v102, 0x3e38aa3b, v114
	s_waitcnt lgkmcnt(0)
	v_fmac_f32_e32 v103, 0x3e38aa3b, v115
	v_max3_f32 v84, v93, v95, v97
	v_max3_f32 v85, v99, v100, v101
	v_max_f32_e32 v86, v102, v103
	v_max3_f32 v84, v86, v84, v85
	v_add_f32_e32 v85, 0x41000000, v82
	v_cmp_gt_f32_e32 vcc, v84, v85
	s_cbranch_vccz .LBB0_265
	v_cmp_lt_i32_e32 vcc, v220, v218
	v_mov_b32_e32 v87, v83
	s_nop 0
	v_cndmask_b32_e32 v85, v212, v220, vcc
	v_lshlrev_b32_e32 v85, 2, v85
	ds_bpermute_b32 v85, v85, v84
	v_cmp_lt_i32_e32 vcc, v219, v218
	v_max_f32_e32 v84, v84, v84
	s_waitcnt lgkmcnt(0)
	v_max_f32_e32 v85, v85, v85
	v_cndmask_b32_e32 v86, v212, v219, vcc
	v_max_f32_e32 v84, v84, v85
	v_lshlrev_b32_e32 v85, 2, v86
	ds_bpermute_b32 v85, v85, v84
	s_waitcnt lgkmcnt(0)
	v_max3_f32 v86, v82, v84, v85
	v_sub_f32_e32 v84, v82, v86
	v_exp_f32_e32 v84, v84
	s_nop 0
	v_mul_f32_e32 v80, v80, v84
	v_mov_b64_e32 v[84:85], v[86:87]
	s_cbranch_execnz .LBB0_220

; template <int MODE>
; __device__ __forceinline__ void nsa_compute(int cur, int buf, int t, int hl, u64 mymask, const bf16x8 (&Qf)[2][2], f32x4 (&O)[4][2], float (&m)[2], float (&l)[2],
;                                             const float (&inv)[2], float* impw, char* lds) {
;     ...
;         const float mxa = fmaxf(fmaxf(sv[0][0], sv[0][1]), sv[0][2]), mxb = fmaxf(fmaxf(sv[0][3], sv[1][0]), sv[1][1]);
;         float mx = fmaxf(fmaxf(fmaxf(sv[1][2], sv[1][3]), mxa), mxb);
;         if (MODE == 2) mx = selok ? mx : -__builtin_inff();
;         if (__any(mx > m[r] + 8.0f)) {
;           mx = fmaxf(mx, __shfl_xor(mx, 16)); mx = fmaxf(mx, __shfl_xor(mx, 32));
;           const float mn = fmaxf(m[r], mx), al = __builtin_amdgcn_exp2f(m[r] - mn);
;           m[r] = mn; l[r] *= al;
;           if (MODE != 0) {
; #pragma unroll
;             for (int df = 0; df < 4; ++df) O[df][r] *= al;
;           }
;         }
;         const float me = (MODE == 2) ? (selok ? m[r] : __builtin_inff()) : m[r];
;         float ps = 0.f;
; #pragma unroll
;         for (int kk = 0; kk < 2; ++kk)
; #pragma unroll
;           for (int e = 0; e < 4; ++e) { pv[kk][e] = __builtin_amdgcn_exp2f(sv[kk][e] - me); ps += pv[kk][e]; }
;         l[r] += ps;
.LBB0_220:
	v_sub_f32_e32 v82, v93, v86
	v_exp_f32_e32 v82, v82
	v_sub_f32_e32 v83, v95, v86
	v_exp_f32_e32 v83, v83
	v_sub_f32_e32 v87, v97, v86
	v_exp_f32_e32 v87, v87
	v_sub_f32_e32 v93, v99, v86
	v_exp_f32_e32 v93, v93
	v_add_f32_e32 v82, v83, v82
	v_sub_f32_e32 v83, v100, v86
	v_add_f32_e32 v82, v87, v82
	v_exp_f32_e32 v83, v83
	v_sub_f32_e32 v87, v101, v86
	v_add_f32_e32 v82, v93, v82
	v_exp_f32_e32 v87, v87
	v_sub_f32_e32 v93, v102, v86
	v_exp_f32_e32 v93, v93
	v_sub_f32_e32 v86, v103, v86
	v_exp_f32_e32 v86, v86
	v_add_f32_e32 v82, v83, v82
	v_add_f32_e32 v82, v87, v82
	v_add_f32_e32 v82, v93, v82
	v_add_f32_e32 v82, v86, v82
	v_add_f32_e32 v80, v80, v82
	ds_read_b32 v88, v88 offset:50432
	ds_read_b32 v89, v89 offset:50432
	ds_read_b32 v90, v90 offset:50432
	ds_read_b32 v91, v91 offset:50432
	ds_read_b32 v82, v92 offset:50432
	ds_read_b32 v83, v94 offset:50432
	ds_read_b32 v86, v96 offset:50432
	ds_read_b32 v87, v98 offset:50432
	s_waitcnt lgkmcnt(7)
	v_fmac_f32_e32 v88, 0x3e38aa3b, v76
	s_waitcnt lgkmcnt(6)
	v_fmac_f32_e32 v89, 0x3e38aa3b, v77
	s_waitcnt lgkmcnt(5)
	v_fmac_f32_e32 v90, 0x3e38aa3b, v78
	s_waitcnt lgkmcnt(4)
	v_fmac_f32_e32 v91, 0x3e38aa3b, v79
	s_waitcnt lgkmcnt(3)
	v_fmac_f32_e32 v82, 0x3e38aa3b, v72
	s_waitcnt lgkmcnt(2)
	v_fmac_f32_e32 v83, 0x3e38aa3b, v73
	s_waitcnt lgkmcnt(1)
	v_fmac_f32_e32 v86, 0x3e38aa3b, v74
	s_waitcnt lgkmcnt(0)
	v_fmac_f32_e32 v87, 0x3e38aa3b, v75
	v_max3_f32 v72, v88, v89, v90
	v_max3_f32 v73, v91, v82, v83
	v_max_f32_e32 v74, v86, v87
	v_max3_f32 v72, v74, v72, v73
	v_add_f32_e32 v73, 0x41000000, v85
	v_cmp_gt_f32_e32 vcc, v72, v73
	s_cbranch_vccz .LBB0_266
	v_cmp_lt_i32_e32 vcc, v220, v218
	s_nop 1
	v_cndmask_b32_e32 v73, v212, v220, vcc
	v_lshlrev_b32_e32 v73, 2, v73
	ds_bpermute_b32 v73, v73, v72
	v_cmp_lt_i32_e32 vcc, v219, v218
	v_max_f32_e32 v72, v72, v72
	s_waitcnt lgkmcnt(0)
	v_max_f32_e32 v73, v73, v73
	v_cndmask_b32_e32 v74, v212, v219, vcc
	v_max_f32_e32 v72, v72, v73
	v_lshlrev_b32_e32 v73, 2, v74
	ds_bpermute_b32 v73, v73, v72
	s_waitcnt lgkmcnt(0)
	v_max3_f32 v73, v85, v72, v73
	v_sub_f32_e32 v72, v85, v73
	v_exp_f32_e32 v74, v72
	v_mov_b32_e32 v72, v84
	v_mov_b64_e32 v[154:155], v[72:73]
	v_mul_f32_e32 v81, v81, v74
	s_cbranch_execnz .LBB0_223

; template <int MODE>
; __device__ __forceinline__ void nsa_compute(int cur, int buf, int t, int hl, u64 mymask, const bf16x8 (&Qf)[2][2], f32x4 (&O)[4][2], float (&m)[2], float (&l)[2],
;                                             const float (&inv)[2], float* impw, char* lds) {
;     ...
; #pragma unroll
;     for (int ks = 0; ks < 2; ++ks)
; #pragma unroll
;       for (int kk = 0; kk < 2; ++kk) kfr[ks][kk] = *(const bf16x8*)(kt + (32 * s2 + 16 * kk + fr) * 128 + (((ks * 4 + fq) ^ (fr & 7)) << 4));
;     __builtin_amdgcn_s_setprio(1);
; #pragma unroll
;     for (int ks = 0; ks < 2; ++ks)
; #pragma unroll
;       for (int kk = 0; kk < 2; ++kk)
; #pragma unroll
;         for (int r = 0; r < 2; ++r) S[kk][r] = mfma16(kfr[ks][kk], Qf[r][ks], S[kk][r]);
;     __builtin_amdgcn_s_setprio(0);
;     bf16x8 Pf[2];
;     float g1s[2] = {0.f, 0.f}, p3s[2] = {0.f, 0.f};
; #pragma unroll
;     for (int r = 0; r < 2; ++r) {
;       float sv[2][4];
; #pragma unroll
;       for (int kk = 0; kk < 2; ++kk)
; #pragma unroll
;         for (int e = 0; e < 4; ++e) {
;           const int off = 32 * s2 + 16 * kk + e;
;           int idx;
;           if (MODE <= 1) { idx = base - 16 * off; idx = idx > 0 ? idx : 0; } else idx = base - off;
;           sv[kk][e] = S[kk][r][e] * (0.125f * LOG2E) + tb[r * TS + idx];
;         }
;       float pv[2][4];
;       if (MODE == 1) {
; #pragma unroll
;         for (int kk = 0; kk < 2; ++kk)
; #pragma unroll
;           for (int e = 0; e < 4; ++e) pv[kk][e] = __builtin_amdgcn_exp2f(sv[kk][e] - m[r]) * inv[r];
; #pragma unroll
;         for (int kk = 0; kk < 2; ++kk) { g1s[kk] += pv[kk][0] + pv[kk][1] + pv[kk][2] + 0.5f * pv[kk][3]; p3s[kk] += 0.5f * pv[kk][3]; }
;       } else {
;         const float mxa = fmaxf(fmaxf(sv[0][0], sv[0][1]), sv[0][2]), mxb = fmaxf(fmaxf(sv[0][3], sv[1][0]), sv[1][1]);
;         float mx = fmaxf(fmaxf(fmaxf(sv[1][2], sv[1][3]), mxa), mxb);
;         if (MODE == 2) mx = selok ? mx : -__builtin_inff();
;         if (__any(mx > m[r] + 8.0f)) {
;           mx = fmaxf(mx, __shfl_xor(mx, 16)); mx = fmaxf(mx, __shfl_xor(mx, 32));
;           const float mn = fmaxf(m[r], mx), al = __builtin_amdgcn_exp2f(m[r] - mn);
;           m[r] = mn; l[r] *= al;
;           if (MODE != 0) {
; #pragma unroll
;             for (int df = 0; df < 4; ++df) O[df][r] *= al;
;           }
;         }
.LBB0_227:
	v_sub_f32_e32 v72, v88, v73
	v_exp_f32_e32 v72, v72
	v_sub_f32_e32 v74, v89, v73
	v_exp_f32_e32 v74, v74
	v_sub_f32_e32 v75, v90, v73
	v_exp_f32_e32 v75, v75
	v_sub_f32_e32 v76, v91, v73
	v_exp_f32_e32 v76, v76
	v_add_f32_e32 v72, v74, v72
	v_sub_f32_e32 v74, v82, v73
	v_add_f32_e32 v72, v75, v72
	v_exp_f32_e32 v74, v74
	v_sub_f32_e32 v75, v83, v73
	v_add_f32_e32 v72, v76, v72
	v_exp_f32_e32 v75, v75
	v_sub_f32_e32 v76, v86, v73
	v_exp_f32_e32 v76, v76
	v_sub_f32_e32 v73, v87, v73
	v_exp_f32_e32 v73, v73
	v_add_f32_e32 v72, v74, v72
	v_add_f32_e32 v72, v75, v72
	v_add_f32_e32 v72, v76, v72
	v_add_f32_e32 v72, v73, v72
	v_add_f32_e32 v81, v81, v72
	s_cmp_lt_i32 s75, 0
	s_mov_b64 vcc, -1
	s_cbranch_scc1 .LBB0_262
	v_mov_b32 v72, v179
	s_lshl_b32 s74, s71, 13
	v_lshrrev_b32_e32 v73, 4, v72
	v_bfe_u32 v86, v72, 4, 2
	v_and_b32_e32 v82, 7, v72
	v_lshlrev_b32_e32 v72, 7, v72
	v_and_b32_e32 v87, 0x780, v72
	v_bitop3_b32 v72, v73, v82, 3 bitop3:0x6c
	v_bitop3_b32 v82, v86, v82, 4 bitop3:0x36
	v_lshl_or_b32 v88, v72, 4, s74
	v_lshl_or_b32 v89, v82, 4, s74
	v_or_b32_e32 v76, v88, v87
	v_or_b32_e32 v90, v89, v87
	ds_read_b128 v[72:75], v76
	ds_read_b128 v[76:79], v76 offset:2048
	ds_read_b128 v[82:85], v90
	ds_read_b128 v[90:93], v90 offset:2048
	v_lshlrev_b32_e32 v86, 6, v86
	v_lshl_or_b32 v86, s75, 10, v86
	v_sub_u32_e32 v86, v183, v86
	s_setprio 1
	s_waitcnt lgkmcnt(3)
	v_mfma_f32_16x16x32_bf16 v[94:97], v[72:75], v[0:3], 0
	v_mfma_f32_16x16x32_bf16 v[72:75], v[72:75], v[8:11], 0
	s_waitcnt lgkmcnt(2)
	v_mfma_f32_16x16x32_bf16 v[98:101], v[76:79], v[0:3], 0
	v_mfma_f32_16x16x32_bf16 v[102:105], v[76:79], v[8:11], 0
	s_waitcnt lgkmcnt(1)
	v_mfma_f32_16x16x32_bf16 v[106:109], v[82:85], v[4:7], v[94:97]
	v_mfma_f32_16x16x32_bf16 v[76:79], v[82:85], v[12:15], v[72:75]
	s_waitcnt lgkmcnt(0)
	v_mfma_f32_16x16x32_bf16 v[82:85], v[90:93], v[4:7], v[98:101]
	v_mfma_f32_16x16x32_bf16 v[72:75], v[90:93], v[12:15], v[102:105]
	s_setprio 0
	v_add_u32_e32 v91, -16, v86
	v_subrev_u32_e32 v92, 32, v86
	v_subrev_u32_e32 v93, 48, v86
	v_add_u32_e32 v94, 0xffffff00, v86
	v_max_i32_e32 v90, 0, v86
	v_max_i32_e32 v91, 0, v91
	v_max_i32_e32 v92, 0, v92
	v_max_i32_e32 v93, 0, v93
	v_max_i32_e32 v94, 0, v94
	v_lshl_add_u32 v90, v90, 2, v181
	v_lshl_add_u32 v91, v91, 2, v181
	v_lshl_add_u32 v92, v92, 2, v181
	v_lshl_add_u32 v93, v93, 2, v181
	v_lshl_add_u32 v94, v94, 2, v181
	ds_read_b32 v95, v90 offset:33792
	ds_read_b32 v97, v91 offset:33792
	ds_read_b32 v99, v92 offset:33792
	ds_read_b32 v101, v93 offset:33792
	ds_read_b32 v102, v94 offset:33792
	s_waitcnt lgkmcnt(4)
	v_fmac_f32_e32 v95, 0x3e38aa3b, v106
	s_waitcnt lgkmcnt(3)
	v_fmac_f32_e32 v97, 0x3e38aa3b, v107
	s_waitcnt lgkmcnt(2)
	v_fmac_f32_e32 v99, 0x3e38aa3b, v108
	s_waitcnt lgkmcnt(1)
	v_fmac_f32_e32 v101, 0x3e38aa3b, v109
	s_waitcnt lgkmcnt(0)
	v_fmac_f32_e32 v102, 0x3e38aa3b, v82
	v_add_u32_e32 v82, 0xfffffef0, v86
	v_max_i32_e32 v82, 0, v82
	v_lshl_add_u32 v96, v82, 2, v181
	v_add_u32_e32 v82, 0xfffffee0, v86
	v_max_i32_e32 v82, 0, v82
	v_lshl_add_u32 v98, v82, 2, v181
	v_add_u32_e32 v82, 0xfffffed0, v86
	v_max_i32_e32 v82, 0, v82
	v_lshl_add_u32 v100, v82, 2, v181
	ds_read_b32 v103, v96 offset:33792
	ds_read_b32 v104, v98 offset:33792
	ds_read_b32 v105, v100 offset:33792
	v_max3_f32 v82, v95, v97, v99
	s_waitcnt lgkmcnt(2)
	v_fmac_f32_e32 v103, 0x3e38aa3b, v83
	s_waitcnt lgkmcnt(1)
	v_fmac_f32_e32 v104, 0x3e38aa3b, v84
	s_waitcnt lgkmcnt(0)
	v_fmac_f32_e32 v105, 0x3e38aa3b, v85
	v_max3_f32 v83, v101, v102, v103
	v_max_f32_e32 v84, v104, v105
	v_max3_f32 v82, v84, v82, v83
	v_add_f32_e32 v83, 0x41000000, v154
	v_cmp_gt_f32_e32 vcc, v82, v83
	s_cbranch_vccz .LBB0_269
	v_cmp_lt_i32_e32 vcc, v220, v218
	s_nop 1
	v_cndmask_b32_e32 v83, v212, v220, vcc
	v_lshlrev_b32_e32 v83, 2, v83
	ds_bpermute_b32 v83, v83, v82
	v_cmp_lt_i32_e32 vcc, v219, v218
	v_max_f32_e32 v82, v82, v82
	s_waitcnt lgkmcnt(0)
	v_max_f32_e32 v83, v83, v83
	v_cndmask_b32_e32 v84, v212, v219, vcc
	v_max_f32_e32 v82, v82, v83
	v_lshlrev_b32_e32 v83, 2, v84
	ds_bpermute_b32 v83, v83, v82
	s_waitcnt lgkmcnt(0)
	v_max3_f32 v82, v154, v82, v83
	v_sub_f32_e32 v83, v154, v82
	v_exp_f32_e32 v84, v83
	v_mov_b32_e32 v83, v155
	v_mul_f32_e32 v80, v80, v84
	v_mov_b64_e32 v[84:85], v[82:83]
	s_cbranch_execnz .LBB0_231

; template <int MODE>
; __device__ __forceinline__ void nsa_compute(int cur, int buf, int t, int hl, u64 mymask, const bf16x8 (&Qf)[2][2], f32x4 (&O)[4][2], float (&m)[2], float (&l)[2],
;                                             const float (&inv)[2], float* impw, char* lds) {
;     ...
; #pragma unroll
;     for (int ks = 0; ks < 2; ++ks)
; #pragma unroll
;       for (int kk = 0; kk < 2; ++kk) kfr[ks][kk] = *(const bf16x8*)(kt + (32 * s2 + 16 * kk + fr) * 128 + (((ks * 4 + fq) ^ (fr & 7)) << 4));
;     __builtin_amdgcn_s_setprio(1);
; #pragma unroll
;     for (int ks = 0; ks < 2; ++ks)
; #pragma unroll
;       for (int kk = 0; kk < 2; ++kk)
; #pragma unroll
;         for (int r = 0; r < 2; ++r) S[kk][r] = mfma16(kfr[ks][kk], Qf[r][ks], S[kk][r]);
;     __builtin_amdgcn_s_setprio(0);
;     bf16x8 Pf[2];
;     float g1s[2] = {0.f, 0.f}, p3s[2] = {0.f, 0.f};
; #pragma unroll
;     for (int r = 0; r < 2; ++r) {
;       float sv[2][4];
; #pragma unroll
;       for (int kk = 0; kk < 2; ++kk)
; #pragma unroll
;         for (int e = 0; e < 4; ++e) {
;           const int off = 32 * s2 + 16 * kk + e;
;           int idx;
;           if (MODE <= 1) { idx = base - 16 * off; idx = idx > 0 ? idx : 0; } else idx = base - off;
;           sv[kk][e] = S[kk][r][e] * (0.125f * LOG2E) + tb[r * TS + idx];
;         }
;       float pv[2][4];
;       if (MODE == 1) {
; #pragma unroll
;         for (int kk = 0; kk < 2; ++kk)
; #pragma unroll
;           for (int e = 0; e < 4; ++e) pv[kk][e] = __builtin_amdgcn_exp2f(sv[kk][e] - m[r]) * inv[r];
; #pragma unroll
;         for (int kk = 0; kk < 2; ++kk) { g1s[kk] += pv[kk][0] + pv[kk][1] + pv[kk][2] + 0.5f * pv[kk][3]; p3s[kk] += 0.5f * pv[kk][3]; }
;       } else {
;         const float mxa = fmaxf(fmaxf(sv[0][0], sv[0][1]), sv[0][2]), mxb = fmaxf(fmaxf(sv[0][3], sv[1][0]), sv[1][1]);
;         float mx = fmaxf(fmaxf(fmaxf(sv[1][2], sv[1][3]), mxa), mxb);
;         if (MODE == 2) mx = selok ? mx : -__builtin_inff();
;         if (__any(mx > m[r] + 8.0f)) {
;           mx = fmaxf(mx, __shfl_xor(mx, 16)); mx = fmaxf(mx, __shfl_xor(mx, 32));
;           const float mn = fmaxf(m[r], mx), al = __builtin_amdgcn_exp2f(m[r] - mn);
;           m[r] = mn; l[r] *= al;
;           if (MODE != 0) {
; #pragma unroll
;             for (int df = 0; df < 4; ++df) O[df][r] *= al;
;           }
;         }
.LBB0_244:
	v_sub_f32_e32 v72, v88, v73
	v_exp_f32_e32 v72, v72
	v_sub_f32_e32 v74, v89, v73
	v_exp_f32_e32 v74, v74
	v_sub_f32_e32 v75, v90, v73
	v_exp_f32_e32 v75, v75
	v_sub_f32_e32 v76, v91, v73
	v_exp_f32_e32 v76, v76
	v_add_f32_e32 v72, v74, v72
	v_sub_f32_e32 v74, v82, v73
	v_add_f32_e32 v72, v75, v72
	v_exp_f32_e32 v74, v74
	v_sub_f32_e32 v75, v83, v73
	v_add_f32_e32 v72, v76, v72
	v_exp_f32_e32 v75, v75
	v_sub_f32_e32 v76, v86, v73
	v_exp_f32_e32 v76, v76
	v_sub_f32_e32 v73, v87, v73
	v_exp_f32_e32 v73, v73
	v_add_f32_e32 v72, v74, v72
	v_add_f32_e32 v72, v75, v72
	v_add_f32_e32 v72, v76, v72
	v_add_f32_e32 v72, v73, v72
	v_add_f32_e32 v81, v81, v72
	s_cmp_lt_i32 s43, 0
	s_mov_b64 vcc, -1
	s_cbranch_scc1 .LBB0_267
	v_mov_b32 v72, v179
	s_nop 0
	v_lshrrev_b32_e32 v73, 4, v72
	v_bfe_u32 v82, v72, 4, 2
	v_and_b32_e32 v83, 7, v72
	v_lshlrev_b32_e32 v72, 7, v72
	v_lshlrev_b32_e32 v74, 6, v82
	v_and_b32_e32 v84, 0x780, v72
	v_bitop3_b32 v72, v73, v83, 3 bitop3:0x6c
	v_bitop3_b32 v82, v82, v83, 4 bitop3:0x36
	v_lshl_add_u32 v72, v72, 4, s72
	v_lshl_add_u32 v82, v82, 4, s72
	v_lshl_or_b32 v74, s43, 10, v74
	v_add_u32_e32 v87, v72, v84
	v_add_u32_e32 v88, v82, v84
	v_sub_u32_e32 v86, v183, v74
	ds_read_b128 v[72:75], v87
	ds_read_b128 v[76:79], v87 offset:2048
	ds_read_b128 v[82:85], v88
	ds_read_b128 v[90:93], v88 offset:2048
	s_setprio 1
	s_waitcnt lgkmcnt(3)
	v_mfma_f32_16x16x32_bf16 v[94:97], v[72:75], v[0:3], 0
	v_mfma_f32_16x16x32_bf16 v[72:75], v[72:75], v[8:11], 0
	s_waitcnt lgkmcnt(2)
	v_mfma_f32_16x16x32_bf16 v[98:101], v[76:79], v[0:3], 0
	v_mfma_f32_16x16x32_bf16 v[102:105], v[76:79], v[8:11], 0
	s_waitcnt lgkmcnt(1)
	v_mfma_f32_16x16x32_bf16 v[106:109], v[82:85], v[4:7], v[94:97]
	v_mfma_f32_16x16x32_bf16 v[76:79], v[82:85], v[12:15], v[72:75]
	s_waitcnt lgkmcnt(0)
	v_mfma_f32_16x16x32_bf16 v[82:85], v[90:93], v[4:7], v[98:101]
	v_mfma_f32_16x16x32_bf16 v[72:75], v[90:93], v[12:15], v[102:105]
	s_setprio 0
	v_add_u32_e32 v90, -16, v86
	v_subrev_u32_e32 v91, 32, v86
	v_subrev_u32_e32 v92, 48, v86
	v_add_u32_e32 v93, 0xffffff00, v86
	v_max_i32_e32 v89, 0, v86
	v_max_i32_e32 v90, 0, v90
	v_max_i32_e32 v91, 0, v91
	v_max_i32_e32 v92, 0, v92
	v_max_i32_e32 v93, 0, v93
	v_lshl_add_u32 v89, v89, 2, v181
	v_lshl_add_u32 v90, v90, 2, v181
	v_lshl_add_u32 v91, v91, 2, v181
	v_lshl_add_u32 v92, v92, 2, v181
	v_lshl_add_u32 v93, v93, 2, v181
	ds_read_b32 v94, v89 offset:33792
	ds_read_b32 v96, v90 offset:33792
	ds_read_b32 v98, v91 offset:33792
	ds_read_b32 v100, v92 offset:33792
	ds_read_b32 v101, v93 offset:33792
	s_waitcnt lgkmcnt(4)
	v_fmac_f32_e32 v94, 0x3e38aa3b, v106
	s_waitcnt lgkmcnt(3)
	v_fmac_f32_e32 v96, 0x3e38aa3b, v107
	s_waitcnt lgkmcnt(2)
	v_fmac_f32_e32 v98, 0x3e38aa3b, v108
	s_waitcnt lgkmcnt(1)
	v_fmac_f32_e32 v100, 0x3e38aa3b, v109
	s_waitcnt lgkmcnt(0)
	v_fmac_f32_e32 v101, 0x3e38aa3b, v82
	v_add_u32_e32 v82, 0xfffffef0, v86
	v_max_i32_e32 v82, 0, v82
	v_lshl_add_u32 v95, v82, 2, v181
	v_add_u32_e32 v82, 0xfffffee0, v86
	v_max_i32_e32 v82, 0, v82
	v_lshl_add_u32 v97, v82, 2, v181
	v_add_u32_e32 v82, 0xfffffed0, v86
	v_max_i32_e32 v82, 0, v82
	v_lshl_add_u32 v99, v82, 2, v181
	ds_read_b32 v102, v95 offset:33792
	ds_read_b32 v103, v97 offset:33792
	ds_read_b32 v104, v99 offset:33792
	v_max3_f32 v82, v94, v96, v98
	s_waitcnt lgkmcnt(2)
	v_fmac_f32_e32 v102, 0x3e38aa3b, v83
	s_waitcnt lgkmcnt(1)
	v_fmac_f32_e32 v103, 0x3e38aa3b, v84
	s_waitcnt lgkmcnt(0)
	v_fmac_f32_e32 v104, 0x3e38aa3b, v85
	v_max3_f32 v83, v100, v101, v102
	v_max_f32_e32 v84, v103, v104
	v_max3_f32 v82, v84, v82, v83
	v_add_f32_e32 v83, 0x41000000, v154
	v_cmp_gt_f32_e32 vcc, v82, v83
	s_cbranch_vccz .LBB0_273
	v_cmp_lt_i32_e32 vcc, v220, v218
	s_nop 1
	v_cndmask_b32_e32 v83, v212, v220, vcc
	v_lshlrev_b32_e32 v83, 2, v83
	ds_bpermute_b32 v83, v83, v82
	v_cmp_lt_i32_e32 vcc, v219, v218
	v_max_f32_e32 v82, v82, v82
	s_waitcnt lgkmcnt(0)
	v_max_f32_e32 v83, v83, v83
	v_cndmask_b32_e32 v84, v212, v219, vcc
	v_max_f32_e32 v82, v82, v83
	v_lshlrev_b32_e32 v83, 2, v84
	ds_bpermute_b32 v83, v83, v82
	s_waitcnt lgkmcnt(0)
	v_max3_f32 v82, v154, v82, v83
	v_sub_f32_e32 v83, v154, v82
	v_exp_f32_e32 v84, v83
	v_mov_b32_e32 v83, v155
	v_mul_f32_e32 v80, v80, v84
	v_mov_b64_e32 v[84:85], v[82:83]
	s_cbranch_execnz .LBB0_248

; template <int MODE>
; __device__ __forceinline__ void nsa_compute(int cur, int buf, int t, int hl, u64 mymask, const bf16x8 (&Qf)[2][2], f32x4 (&O)[4][2], float (&m)[2], float (&l)[2],
;                                             const float (&inv)[2], float* impw, char* lds) {
;     ...
;         const float mxa = fmaxf(fmaxf(sv[0][0], sv[0][1]), sv[0][2]), mxb = fmaxf(fmaxf(sv[0][3], sv[1][0]), sv[1][1]);
;         float mx = fmaxf(fmaxf(fmaxf(sv[1][2], sv[1][3]), mxa), mxb);
;         if (MODE == 2) mx = selok ? mx : -__builtin_inff();
;         if (__any(mx > m[r] + 8.0f)) {
;           mx = fmaxf(mx, __shfl_xor(mx, 16)); mx = fmaxf(mx, __shfl_xor(mx, 32));
;           const float mn = fmaxf(m[r], mx), al = __builtin_amdgcn_exp2f(m[r] - mn);
;           m[r] = mn; l[r] *= al;
;           if (MODE != 0) {
; #pragma unroll
;             for (int df = 0; df < 4; ++df) O[df][r] *= al;
;           }
;         }
;         const float me = (MODE == 2) ? (selok ? m[r] : __builtin_inff()) : m[r];
;         float ps = 0.f;
; #pragma unroll
;         for (int kk = 0; kk < 2; ++kk)
; #pragma unroll
;           for (int e = 0; e < 4; ++e) { pv[kk][e] = __builtin_amdgcn_exp2f(sv[kk][e] - me); ps += pv[kk][e]; }
;         l[r] += ps;
.LBB0_248:
	v_sub_f32_e32 v83, v94, v82
	v_exp_f32_e32 v83, v83
	v_sub_f32_e32 v94, v96, v82
	v_exp_f32_e32 v94, v94
	v_sub_f32_e32 v96, v98, v82
	v_exp_f32_e32 v96, v96
	v_sub_f32_e32 v98, v100, v82
	v_exp_f32_e32 v98, v98
	v_add_f32_e32 v83, v94, v83
	v_sub_f32_e32 v94, v101, v82
	v_add_f32_e32 v83, v96, v83
	v_exp_f32_e32 v94, v94
	v_sub_f32_e32 v96, v102, v82
	v_add_f32_e32 v83, v98, v83
	v_exp_f32_e32 v96, v96
	v_sub_f32_e32 v98, v103, v82
	v_exp_f32_e32 v98, v98
	v_add_f32_e32 v83, v94, v83
	v_add_f32_e32 v83, v96, v83
	v_sub_f32_e32 v82, v104, v82
	v_add_f32_e32 v83, v98, v83
	ds_read_b32 v100, v89 offset:50432
	ds_read_b32 v98, v90 offset:50432
	ds_read_b32 v96, v91 offset:50432
	ds_read_b32 v94, v92 offset:50432
	ds_read_b32 v92, v93 offset:50432
	ds_read_b32 v91, v95 offset:50432
	ds_read_b32 v90, v97 offset:50432
	ds_read_b32 v89, v99 offset:50432
	v_exp_f32_e32 v82, v82
	s_waitcnt lgkmcnt(7)
	v_fmac_f32_e32 v100, 0x3e38aa3b, v76
	s_waitcnt lgkmcnt(6)
	v_fmac_f32_e32 v98, 0x3e38aa3b, v77
	s_waitcnt lgkmcnt(5)
	v_fmac_f32_e32 v96, 0x3e38aa3b, v78
	s_waitcnt lgkmcnt(4)
	v_fmac_f32_e32 v94, 0x3e38aa3b, v79
	s_waitcnt lgkmcnt(3)
	v_fmac_f32_e32 v92, 0x3e38aa3b, v72
	s_waitcnt lgkmcnt(2)
	v_fmac_f32_e32 v91, 0x3e38aa3b, v73
	s_waitcnt lgkmcnt(1)
	v_fmac_f32_e32 v90, 0x3e38aa3b, v74
	s_waitcnt lgkmcnt(0)
	v_fmac_f32_e32 v89, 0x3e38aa3b, v75
	v_max3_f32 v72, v100, v98, v96
	v_max3_f32 v73, v94, v92, v91
	v_max_f32_e32 v74, v90, v89
	v_add_f32_e32 v82, v82, v83
	v_max3_f32 v72, v74, v72, v73
	v_add_f32_e32 v73, 0x41000000, v85
	v_add_f32_e32 v80, v80, v82
	v_cmp_gt_f32_e32 vcc, v72, v73
	s_cbranch_vccz .LBB0_274
	v_cmp_lt_i32_e32 vcc, v220, v218
	s_nop 1
	v_cndmask_b32_e32 v73, v212, v220, vcc
	v_lshlrev_b32_e32 v73, 2, v73
	ds_bpermute_b32 v73, v73, v72
	v_cmp_lt_i32_e32 vcc, v219, v218
	v_max_f32_e32 v72, v72, v72
	s_waitcnt lgkmcnt(0)
	v_max_f32_e32 v73, v73, v73
	v_cndmask_b32_e32 v74, v212, v219, vcc
	v_max_f32_e32 v72, v72, v73
	v_lshlrev_b32_e32 v73, 2, v74
	ds_bpermute_b32 v73, v73, v72
	s_waitcnt lgkmcnt(0)
	v_max3_f32 v73, v85, v72, v73
	v_sub_f32_e32 v72, v85, v73
	v_exp_f32_e32 v74, v72
	v_mov_b32_e32 v72, v84
	v_mov_b64_e32 v[82:83], v[72:73]
	v_mul_f32_e32 v81, v81, v74
	s_cbranch_execnz .LBB0_251

; template <int MODE>
; __device__ __forceinline__ void nsa_compute(int cur, int buf, int t, int hl, u64 mymask, const bf16x8 (&Qf)[2][2], f32x4 (&O)[4][2], float (&m)[2], float (&l)[2],
;                                             const float (&inv)[2], float* impw, char* lds) {
;     ...
; #pragma unroll
;     for (int ks = 0; ks < 2; ++ks)
; #pragma unroll
;       for (int kk = 0; kk < 2; ++kk) kfr[ks][kk] = *(const bf16x8*)(kt + (32 * s2 + 16 * kk + fr) * 128 + (((ks * 4 + fq) ^ (fr & 7)) << 4));
;     __builtin_amdgcn_s_setprio(1);
; #pragma unroll
;     for (int ks = 0; ks < 2; ++ks)
; #pragma unroll
;       for (int kk = 0; kk < 2; ++kk)
; #pragma unroll
;         for (int r = 0; r < 2; ++r) S[kk][r] = mfma16(kfr[ks][kk], Qf[r][ks], S[kk][r]);
;     __builtin_amdgcn_s_setprio(0);
;     bf16x8 Pf[2];
;     float g1s[2] = {0.f, 0.f}, p3s[2] = {0.f, 0.f};
; #pragma unroll
;     for (int r = 0; r < 2; ++r) {
;       float sv[2][4];
; #pragma unroll
;       for (int kk = 0; kk < 2; ++kk)
; #pragma unroll
;         for (int e = 0; e < 4; ++e) {
;           const int off = 32 * s2 + 16 * kk + e;
;           int idx;
;           if (MODE <= 1) { idx = base - 16 * off; idx = idx > 0 ? idx : 0; } else idx = base - off;
;           sv[kk][e] = S[kk][r][e] * (0.125f * LOG2E) + tb[r * TS + idx];
;         }
;       float pv[2][4];
;       if (MODE == 1) {
; #pragma unroll
;         for (int kk = 0; kk < 2; ++kk)
; #pragma unroll
;           for (int e = 0; e < 4; ++e) pv[kk][e] = __builtin_amdgcn_exp2f(sv[kk][e] - m[r]) * inv[r];
; #pragma unroll
;         for (int kk = 0; kk < 2; ++kk) { g1s[kk] += pv[kk][0] + pv[kk][1] + pv[kk][2] + 0.5f * pv[kk][3]; p3s[kk] += 0.5f * pv[kk][3]; }
;       } else {
;         const float mxa = fmaxf(fmaxf(sv[0][0], sv[0][1]), sv[0][2]), mxb = fmaxf(fmaxf(sv[0][3], sv[1][0]), sv[1][1]);
;         float mx = fmaxf(fmaxf(fmaxf(sv[1][2], sv[1][3]), mxa), mxb);
;         if (MODE == 2) mx = selok ? mx : -__builtin_inff();
;         if (__any(mx > m[r] + 8.0f)) {
;           mx = fmaxf(mx, __shfl_xor(mx, 16)); mx = fmaxf(mx, __shfl_xor(mx, 32));
;           const float mn = fmaxf(m[r], mx), al = __builtin_amdgcn_exp2f(m[r] - mn);
;           m[r] = mn; l[r] *= al;
;           if (MODE != 0) {
; #pragma unroll
;             for (int df = 0; df < 4; ++df) O[df][r] *= al;
;           }
;         }
.LBB0_251:
	v_sub_f32_e32 v72, v100, v73
	v_exp_f32_e32 v72, v72
	v_sub_f32_e32 v74, v98, v73
	v_exp_f32_e32 v74, v74
	s_nop 0
	v_add_f32_e32 v72, v74, v72
	v_sub_f32_e32 v74, v96, v73
	v_exp_f32_e32 v74, v74
	s_nop 0
	v_add_f32_e32 v72, v74, v72
	v_sub_f32_e32 v74, v94, v73
	v_exp_f32_e32 v74, v74
	s_nop 0
	v_add_f32_e32 v72, v74, v72
	v_sub_f32_e32 v74, v92, v73
	v_exp_f32_e32 v74, v74
	s_nop 0
	v_add_f32_e32 v72, v74, v72
	v_sub_f32_e32 v74, v91, v73
	v_exp_f32_e32 v74, v74
	s_nop 0
	v_add_f32_e32 v72, v74, v72
	v_sub_f32_e32 v74, v90, v73
	v_exp_f32_e32 v74, v74
	v_sub_f32_e32 v73, v89, v73
	v_exp_f32_e32 v73, v73
	v_add_f32_e32 v72, v74, v72
	v_add_f32_e32 v72, v73, v72
	v_add_f32_e32 v81, v81, v72
	ds_read_b128 v[72:75], v87 offset:4096
	ds_read_b128 v[76:79], v87 offset:6144
	ds_read_b128 v[90:93], v88 offset:4096
	ds_read_b128 v[94:97], v88 offset:6144
	s_setprio 1
	s_waitcnt lgkmcnt(3)
	v_mfma_f32_16x16x32_bf16 v[98:101], v[72:75], v[0:3], 0
	v_mfma_f32_16x16x32_bf16 v[72:75], v[72:75], v[8:11], 0
	s_waitcnt lgkmcnt(2)
	v_mfma_f32_16x16x32_bf16 v[102:105], v[76:79], v[0:3], 0
	v_mfma_f32_16x16x32_bf16 v[106:109], v[76:79], v[8:11], 0
	s_waitcnt lgkmcnt(1)
	v_mfma_f32_16x16x32_bf16 v[98:101], v[90:93], v[4:7], v[98:101]
	v_mfma_f32_16x16x32_bf16 v[76:79], v[90:93], v[12:15], v[72:75]
	s_waitcnt lgkmcnt(0)
	v_mfma_f32_16x16x32_bf16 v[102:105], v[94:97], v[4:7], v[102:105]
	v_mfma_f32_16x16x32_bf16 v[72:75], v[94:97], v[12:15], v[106:109]
	s_setprio 0
	v_add_u32_e32 v84, 0xfffffe00, v86
	v_max_i32_e32 v84, 0, v84
	v_lshl_add_u32 v88, v84, 2, v181
	v_add_u32_e32 v84, 0xfffffdf0, v86
	v_max_i32_e32 v84, 0, v84
	v_lshl_add_u32 v89, v84, 2, v181
	ds_read_b32 v93, v88 offset:33792
	ds_read_b32 v95, v89 offset:33792
	v_add_u32_e32 v84, 0xfffffde0, v86
	v_max_i32_e32 v84, 0, v84
	v_lshl_add_u32 v90, v84, 2, v181
	v_add_u32_e32 v84, 0xfffffdd0, v86
	v_max_i32_e32 v84, 0, v84
	v_lshl_add_u32 v91, v84, 2, v181
	ds_read_b32 v97, v90 offset:33792
	s_waitcnt lgkmcnt(1)
	v_fmac_f32_e32 v95, 0x3e38aa3b, v99
	ds_read_b32 v99, v91 offset:33792
	v_add_u32_e32 v84, 0xfffffd00, v86
	v_max_i32_e32 v84, 0, v84
	v_lshl_add_u32 v92, v84, 2, v181
	v_add_u32_e32 v84, 0xfffffcf0, v86
	v_max_i32_e32 v84, 0, v84
	v_lshl_add_u32 v94, v84, 2, v181
	s_waitcnt lgkmcnt(1)
	v_fmac_f32_e32 v97, 0x3e38aa3b, v100
	ds_read_b32 v100, v92 offset:33792
	s_waitcnt lgkmcnt(1)
	v_fmac_f32_e32 v99, 0x3e38aa3b, v101
	ds_read_b32 v101, v94 offset:33792
	v_add_u32_e32 v84, 0xfffffce0, v86
	v_max_i32_e32 v84, 0, v84
	v_lshl_add_u32 v96, v84, 2, v181
	v_add_u32_e32 v84, 0xfffffcd0, v86
	v_max_i32_e32 v84, 0, v84
	v_fmac_f32_e32 v93, 0x3e38aa3b, v98
	v_lshl_add_u32 v98, v84, 2, v181
	s_waitcnt lgkmcnt(1)
	v_fmac_f32_e32 v100, 0x3e38aa3b, v102
	ds_read_b32 v102, v96 offset:33792
	s_waitcnt lgkmcnt(1)
	v_fmac_f32_e32 v101, 0x3e38aa3b, v103
	ds_read_b32 v103, v98 offset:33792
	v_max3_f32 v84, v93, v95, v97
	v_max3_f32 v85, v99, v100, v101
	s_waitcnt lgkmcnt(1)
	v_fmac_f32_e32 v102, 0x3e38aa3b, v104
	s_waitcnt lgkmcnt(0)
	v_fmac_f32_e32 v103, 0x3e38aa3b, v105
	v_max_f32_e32 v86, v102, v103
	v_max3_f32 v84, v86, v84, v85
	v_add_f32_e32 v85, 0x41000000, v82
	v_cmp_gt_f32_e32 vcc, v84, v85
	s_cbranch_vccz .LBB0_275
	v_cmp_lt_i32_e32 vcc, v220, v218
	v_mov_b32_e32 v87, v83
	s_nop 0
	v_cndmask_b32_e32 v85, v212, v220, vcc
	v_lshlrev_b32_e32 v85, 2, v85
	ds_bpermute_b32 v85, v85, v84
	v_cmp_lt_i32_e32 vcc, v219, v218
	v_max_f32_e32 v84, v84, v84
	s_waitcnt lgkmcnt(0)
	v_max_f32_e32 v85, v85, v85
	v_cndmask_b32_e32 v86, v212, v219, vcc
	v_max_f32_e32 v84, v84, v85
	v_lshlrev_b32_e32 v85, 2, v86
	ds_bpermute_b32 v85, v85, v84
	s_waitcnt lgkmcnt(0)
	v_max3_f32 v86, v82, v84, v85
	v_sub_f32_e32 v84, v82, v86
	v_exp_f32_e32 v84, v84
	s_nop 0
	v_mul_f32_e32 v80, v80, v84
	v_mov_b64_e32 v[84:85], v[86:87]
	s_cbranch_execnz .LBB0_254

; template <int MODE>
; __device__ __forceinline__ void nsa_compute(int cur, int buf, int t, int hl, u64 mymask, const bf16x8 (&Qf)[2][2], f32x4 (&O)[4][2], float (&m)[2], float (&l)[2],
;                                             const float (&inv)[2], float* impw, char* lds) {
;     ...
;         float ps = 0.f;
; #pragma unroll
;         for (int kk = 0; kk < 2; ++kk)
; #pragma unroll
;           for (int e = 0; e < 4; ++e) { pv[kk][e] = __builtin_amdgcn_exp2f(sv[kk][e] - me); ps += pv[kk][e]; }
;         l[r] += ps;
; template <int MODE> ...
;     ...
;   for (;;) {
;     NSA_STEP(R1)
;     NSA_STEP(R2)
;     NSA_STEP(R0)
.LBB0_261:
	v_sub_f32_e32 v72, v88, v73
	v_exp_f32_e32 v72, v72
	v_sub_f32_e32 v74, v89, v73
	v_exp_f32_e32 v74, v74
	v_sub_f32_e32 v75, v90, v73
	v_exp_f32_e32 v75, v75
	v_sub_f32_e32 v76, v91, v73
	v_exp_f32_e32 v76, v76
	v_add_f32_e32 v72, v74, v72
	v_sub_f32_e32 v74, v82, v73
	v_add_f32_e32 v72, v75, v72
	v_exp_f32_e32 v74, v74
	v_sub_f32_e32 v75, v83, v73
	v_add_f32_e32 v72, v76, v72
	v_exp_f32_e32 v75, v75
	v_sub_f32_e32 v76, v86, v73
	v_exp_f32_e32 v76, v76
	v_sub_f32_e32 v73, v87, v73
	v_exp_f32_e32 v73, v73
	s_add_i32 s31, s73, 1
	v_add_f32_e32 v72, v74, v72
	s_and_b64 s[42:43], s[42:43], exec
	v_add_f32_e32 v72, v75, v72
	s_cselect_b32 s31, s31, -1
	v_add_f32_e32 v72, v76, v72
	s_cmp_lt_i32 s69, 0
	v_add_f32_e32 v72, v73, v72
	s_cselect_b64 vcc, -1, 0
	s_add_u32 s34, s34, 0x6000
	v_add_f32_e32 v81, v81, v72
	s_addc_u32 s35, s35, 0
	s_add_i32 s42, s73, 2
	s_add_i32 s70, s70, -3
	s_and_b64 vcc, exec, vcc
	s_cbranch_vccz .LBB0_268
	s_branch .LBB0_278

; template <int MODE>
; __device__ __forceinline__ void nsa_compute(int cur, int buf, int t, int hl, u64 mymask, const bf16x8 (&Qf)[2][2], f32x4 (&O)[4][2], float (&m)[2], float (&l)[2],
;                                             const float (&inv)[2], float* impw, char* lds) {
;     ...
;     for (int r = 0; r < 2; ++r) {
;       float sv[2][4];
; #pragma unroll
;       for (int kk = 0; kk < 2; ++kk)
; #pragma unroll
;         for (int e = 0; e < 4; ++e) {
;           const int off = 32 * s2 + 16 * kk + e;
;           int idx;
;           if (MODE <= 1) { idx = base - 16 * off; idx = idx > 0 ? idx : 0; } else idx = base - off;
;           sv[kk][e] = S[kk][r][e] * (0.125f * LOG2E) + tb[r * TS + idx];
;         }
;       float pv[2][4];
;       if (MODE == 1) {
; #pragma unroll
;         for (int kk = 0; kk < 2; ++kk)
; #pragma unroll
;           for (int e = 0; e < 4; ++e) pv[kk][e] = __builtin_amdgcn_exp2f(sv[kk][e] - m[r]) * inv[r];
; #pragma unroll
;         for (int kk = 0; kk < 2; ++kk) { g1s[kk] += pv[kk][0] + pv[kk][1] + pv[kk][2] + 0.5f * pv[kk][3]; p3s[kk] += 0.5f * pv[kk][3]; }
;       } else {
;         const float mxa = fmaxf(fmaxf(sv[0][0], sv[0][1]), sv[0][2]), mxb = fmaxf(fmaxf(sv[0][3], sv[1][0]), sv[1][1]);
;         float mx = fmaxf(fmaxf(fmaxf(sv[1][2], sv[1][3]), mxa), mxb);
;         if (MODE == 2) mx = selok ? mx : -__builtin_inff();
;         if (__any(mx > m[r] + 8.0f)) {
;           mx = fmaxf(mx, __shfl_xor(mx, 16)); mx = fmaxf(mx, __shfl_xor(mx, 32));
;           const float mn = fmaxf(m[r], mx), al = __builtin_amdgcn_exp2f(m[r] - mn);
;           m[r] = mn; l[r] *= al;
;           if (MODE != 0) {
; #pragma unroll
;             for (int df = 0; df < 4; ++df) O[df][r] *= al;
;           }
;         }
;         const float me = (MODE == 2) ? (selok ? m[r] : __builtin_inff()) : m[r];
;         float ps = 0.f;
; #pragma unroll
;         for (int kk = 0; kk < 2; ++kk)
; #pragma unroll
;           for (int e = 0; e < 4; ++e) { pv[kk][e] = __builtin_amdgcn_exp2f(sv[kk][e] - me); ps += pv[kk][e]; }
;         l[r] += ps;
.LBB0_364:
	v_sub_f32_e32 v85, v94, v88
	v_exp_f32_e32 v85, v85
	v_sub_f32_e32 v86, v86, v88
	v_exp_f32_e32 v86, v86
	v_sub_f32_e32 v87, v87, v88
	v_exp_f32_e32 v87, v87
	v_sub_f32_e32 v84, v84, v88
	v_exp_f32_e32 v84, v84
	v_add_f32_e32 v89, v86, v85
	v_add_f32_e32 v89, v87, v89
	v_sub_f32_e32 v81, v81, v88
	v_add_f32_e32 v94, v84, v89
	v_exp_f32_e32 v89, v81
	v_sub_f32_e32 v80, v80, v88
	v_add_f32_e32 v81, v89, v94
	v_exp_f32_e32 v94, v80
	s_nop 0
	v_add_f32_e32 v80, v94, v81
	v_sub_f32_e32 v81, v83, v88
	v_exp_f32_e32 v95, v81
	v_sub_f32_e32 v81, v82, v88
	v_exp_f32_e32 v88, v81
	v_add_f32_e32 v80, v95, v80
	v_add_f32_e32 v80, v88, v80
	v_add_f32_e32 v190, v190, v80
	s_waitcnt lgkmcnt(3)
	v_fmamk_f32 v81, v76, 0x3e38aa3b, v173
	v_fmamk_f32 v80, v77, 0x3e38aa3b, v172
	s_waitcnt lgkmcnt(2)
	v_fmamk_f32 v78, v78, 0x3e38aa3b, v175
	v_fmamk_f32 v82, v79, 0x3e38aa3b, v174
	s_waitcnt lgkmcnt(1)
	v_fmamk_f32 v77, v72, 0x3e38aa3b, v195
	v_fmamk_f32 v76, v73, 0x3e38aa3b, v194
	s_waitcnt lgkmcnt(0)
	v_fmamk_f32 v73, v74, 0x3e38aa3b, v199
	v_fmamk_f32 v72, v75, 0x3e38aa3b, v198
	v_max3_f32 v74, v81, v80, v78
	v_max3_f32 v75, v82, v77, v76
	v_max_f32_e32 v79, v73, v72
	v_max3_f32 v74, v79, v74, v75
	v_add_f32_e32 v75, 0x41000000, v193
	v_cmp_gt_f32_e32 vcc, v74, v75
	s_cbranch_vccz .LBB0_366
	ds_bpermute_b32 v75, v233, v74
	v_max_f32_e32 v74, v74, v74
	s_waitcnt lgkmcnt(0)
	v_max_f32_e32 v75, v75, v75
	v_max_f32_e32 v74, v74, v75
	ds_bpermute_b32 v75, v234, v74
	s_waitcnt lgkmcnt(0)
	v_max3_f32 v74, v193, v74, v75
	v_sub_f32_e32 v75, v193, v74
	v_exp_f32_e32 v96, v75
	v_mov_b32_e32 v193, v74
	v_mul_f32_e32 v191, v191, v96
	v_pk_mul_f32 v[106:107], v[106:107], v[96:97] op_sel_hi:[1,0]
	v_pk_mul_f32 v[104:105], v[104:105], v[96:97] op_sel_hi:[1,0]
	v_pk_mul_f32 v[110:111], v[110:111], v[96:97] op_sel_hi:[1,0]
	v_pk_mul_f32 v[108:109], v[108:109], v[96:97] op_sel_hi:[1,0]
	v_pk_mul_f32 v[114:115], v[114:115], v[96:97] op_sel_hi:[1,0]
	v_pk_mul_f32 v[112:113], v[112:113], v[96:97] op_sel_hi:[1,0]
	v_pk_mul_f32 v[122:123], v[122:123], v[96:97] op_sel_hi:[1,0]
	v_pk_mul_f32 v[120:121], v[120:121], v[96:97] op_sel_hi:[1,0]
	s_branch .LBB0_367

; template <int MODE>
; __device__ __forceinline__ void nsa_compute(int cur, int buf, int t, int hl, u64 mymask, const bf16x8 (&Qf)[2][2], f32x4 (&O)[4][2], float (&m)[2], float (&l)[2],
;                                             const float (&inv)[2], float* impw, char* lds) {
;     ...
;     for (int r = 0; r < 2; ++r) {
;       float sv[2][4];
; #pragma unroll
;       for (int kk = 0; kk < 2; ++kk)
; #pragma unroll
;         for (int e = 0; e < 4; ++e) {
;           const int off = 32 * s2 + 16 * kk + e;
;           int idx;
;           if (MODE <= 1) { idx = base - 16 * off; idx = idx > 0 ? idx : 0; } else idx = base - off;
;           sv[kk][e] = S[kk][r][e] * (0.125f * LOG2E) + tb[r * TS + idx];
;         }
;       float pv[2][4];
;       if (MODE == 1) {
; #pragma unroll
;         for (int kk = 0; kk < 2; ++kk)
; #pragma unroll
;           for (int e = 0; e < 4; ++e) pv[kk][e] = __builtin_amdgcn_exp2f(sv[kk][e] - m[r]) * inv[r];
; #pragma unroll
;         for (int kk = 0; kk < 2; ++kk) { g1s[kk] += pv[kk][0] + pv[kk][1] + pv[kk][2] + 0.5f * pv[kk][3]; p3s[kk] += 0.5f * pv[kk][3]; }
;       } else {
;         const float mxa = fmaxf(fmaxf(sv[0][0], sv[0][1]), sv[0][2]), mxb = fmaxf(fmaxf(sv[0][3], sv[1][0]), sv[1][1]);
;         float mx = fmaxf(fmaxf(fmaxf(sv[1][2], sv[1][3]), mxa), mxb);
;         if (MODE == 2) mx = selok ? mx : -__builtin_inff();
;         if (__any(mx > m[r] + 8.0f)) {
;           mx = fmaxf(mx, __shfl_xor(mx, 16)); mx = fmaxf(mx, __shfl_xor(mx, 32));
;           const float mn = fmaxf(m[r], mx), al = __builtin_amdgcn_exp2f(m[r] - mn);
;           m[r] = mn; l[r] *= al;
;           if (MODE != 0) {
; #pragma unroll
;             for (int df = 0; df < 4; ++df) O[df][r] *= al;
;           }
;         }
;         const float me = (MODE == 2) ? (selok ? m[r] : __builtin_inff()) : m[r];
;         float ps = 0.f;
; #pragma unroll
;         for (int kk = 0; kk < 2; ++kk)
; #pragma unroll
;           for (int e = 0; e < 4; ++e) { pv[kk][e] = __builtin_amdgcn_exp2f(sv[kk][e] - me); ps += pv[kk][e]; }
;         l[r] += ps;
;       }
;       if (MODE != 0) {
;         const unsigned w0 = pk2(pv[0][0], pv[0][1]), w1 = pk2(pv[0][2], pv[0][3]), w2 = pk2(pv[1][0], pv[1][1]), w3 = pk2(pv[1][2], pv[1][3]);
;         u32x4 pw; pw.x = w0; pw.y = w1; pw.z = w2; pw.w = w3;
;         Pf[r] = __builtin_bit_cast(bf16x8, pw);
;       }
;     }
.LBB0_367:
	v_sub_f32_e32 v75, v81, v74
	v_exp_f32_e32 v75, v75
	v_sub_f32_e32 v80, v80, v74
	v_exp_f32_e32 v80, v80
	v_sub_f32_e32 v78, v78, v74
	v_exp_f32_e32 v78, v78
	v_sub_f32_e32 v81, v82, v74
	v_exp_f32_e32 v81, v81
	v_sub_f32_e32 v77, v77, v74
	v_exp_f32_e32 v77, v77
	v_sub_f32_e32 v76, v76, v74
	v_add_f32_e32 v79, v80, v75
	v_exp_f32_e32 v76, v76
	v_sub_f32_e32 v73, v73, v74
	v_add_f32_e32 v79, v78, v79
	v_exp_f32_e32 v73, v73
	v_sub_f32_e32 v72, v72, v74
	v_add_f32_e32 v79, v81, v79
	v_exp_f32_e32 v72, v72
	v_add_f32_e32 v79, v77, v79
	v_add_f32_e32 v79, v76, v79
	v_add_f32_e32 v79, v73, v79
	s_lshl_b32 s17, s46, 9
	v_add_f32_e32 v74, v72, v79
	v_cvt_pk_bf16_f32 v149, v73, v72
	v_mul_u32_u24_e32 v72, 0x44, v92
	s_add_i32 s43, s64, s17
	v_lshlrev_b32_e32 v72, 1, v72
	v_lshlrev_b32_e32 v73, 1, v93
	v_cvt_pk_bf16_f32 v146, v75, v80
	v_add3_u32 v80, s43, v72, v73
	v_add_u32_e32 v137, 0x4000, v80
	v_add_u32_e32 v138, 0x4800, v80
	v_add_f32_e32 v191, v191, v74
	v_cvt_pk_bf16_f32 v147, v78, v81
	v_cvt_pk_bf16_f32 v148, v77, v76
	ds_read2_b64 v[72:75], v137 offset1:4
	ds_read2_b64 v[76:79], v138 offset0:16 offset1:20
	v_add_u32_e32 v139, 0x5000, v80
	v_add_u32_e32 v140, 0x5800, v80
	ds_read2_b64 v[150:153], v139 offset0:32 offset1:36
	ds_read2_b64 v[154:157], v140 offset0:48 offset1:52
	v_cvt_pk_bf16_f32 v142, v85, v86
	v_cvt_pk_bf16_f32 v143, v87, v84
	v_cvt_pk_bf16_f32 v144, v89, v94
	v_cvt_pk_bf16_f32 v145, v95, v88
	s_setprio 1
	s_waitcnt lgkmcnt(3)
	v_mfma_f32_16x16x32_bf16 v[84:87], v[72:75], v[142:145], v[116:119]
	v_mfma_f32_16x16x32_bf16 v[96:99], v[72:75], v[146:149], v[104:107]
	s_waitcnt lgkmcnt(2)
	v_mfma_f32_16x16x32_bf16 v[80:83], v[76:79], v[142:145], v[124:127]
	v_mfma_f32_16x16x32_bf16 v[92:95], v[76:79], v[146:149], v[108:111]
	s_waitcnt lgkmcnt(1)
	v_mfma_f32_16x16x32_bf16 v[76:79], v[150:153], v[142:145], v[128:131]
	v_mfma_f32_16x16x32_bf16 v[108:111], v[150:153], v[146:149], v[112:115]
	s_waitcnt lgkmcnt(0)
	v_mfma_f32_16x16x32_bf16 v[72:75], v[154:157], v[142:145], v[132:135]
	v_mfma_f32_16x16x32_bf16 v[104:107], v[154:157], v[146:149], v[120:123]
	s_setprio 0
	v_add_u32_e32 v88, v91, v90
	v_add_u32_e32 v100, v100, v90
	ds_read_b128 v[112:115], v88 offset:4096
	ds_read_b128 v[116:119], v88 offset:6144
	ds_read_b128 v[88:91], v100 offset:4096
	ds_read_b128 v[120:123], v100 offset:6144
	v_add_u32_e32 v251, 0xa00, v136
	ds_read2_b32 v[168:169], v136 offset0:31 offset1:32
	ds_read2_b32 v[170:171], v136 offset0:29 offset1:30
	ds_read2_b32 v[172:173], v136 offset0:15 offset1:16
	ds_read2_b32 v[174:175], v136 offset0:13 offset1:14
	ds_read2_b32 v[198:199], v251 offset0:31 offset1:32
	ds_read2_b32 v[200:201], v251 offset0:29 offset1:30
	ds_read2_b32 v[202:203], v251 offset0:15 offset1:16
	ds_read2_b32 v[204:205], v251 offset0:13 offset1:14
	s_setprio 1
	s_waitcnt lgkmcnt(11)
	v_mfma_f32_16x16x32_bf16 v[100:103], v[112:115], v[0:3], 0
	v_mfma_f32_16x16x32_bf16 v[112:115], v[112:115], v[8:11], 0
	s_waitcnt lgkmcnt(10)
	v_mfma_f32_16x16x32_bf16 v[124:127], v[116:119], v[0:3], 0
	v_mfma_f32_16x16x32_bf16 v[116:119], v[116:119], v[8:11], 0
	s_waitcnt lgkmcnt(9)
	v_mfma_f32_16x16x32_bf16 v[128:131], v[88:91], v[4:7], v[100:103]
	v_mfma_f32_16x16x32_bf16 v[100:103], v[88:91], v[12:15], v[112:115]
	s_waitcnt lgkmcnt(8)
	v_mfma_f32_16x16x32_bf16 v[88:91], v[120:123], v[12:15], v[116:119]
	v_mfma_f32_16x16x32_bf16 v[124:127], v[120:123], v[4:7], v[124:127]
	s_setprio 0
	s_nop 0
	s_waitcnt lgkmcnt(7)
	s_nop 0
	v_fmamk_f32 v123, v128, 0x3e38aa3b, v169
	v_fmamk_f32 v118, v129, 0x3e38aa3b, v168
	s_waitcnt lgkmcnt(6)
	v_fmamk_f32 v122, v130, 0x3e38aa3b, v171
	v_fmamk_f32 v116, v131, 0x3e38aa3b, v170
	s_waitcnt lgkmcnt(5)
	v_fmamk_f32 v119, v124, 0x3e38aa3b, v173
	v_fmamk_f32 v114, v125, 0x3e38aa3b, v172
	s_waitcnt lgkmcnt(4)
	v_fmamk_f32 v113, v126, 0x3e38aa3b, v175
	v_fmamk_f32 v112, v127, 0x3e38aa3b, v174
	v_max3_f32 v115, v123, v118, v122
	v_max3_f32 v117, v116, v119, v114
	v_max_f32_e32 v120, v113, v112
	v_max3_f32 v115, v120, v115, v117
	v_add_f32_e32 v117, 0x41000000, v192
	v_cmp_gt_f32_e32 vcc, v115, v117
	s_cbranch_vccz .LBB0_369
	ds_bpermute_b32 v117, v233, v115
	v_max_f32_e32 v115, v115, v115
	v_mov_b32_e32 v121, v193
	s_waitcnt lgkmcnt(0)
	v_max_f32_e32 v117, v117, v117
	v_max_f32_e32 v115, v115, v117
	ds_bpermute_b32 v117, v234, v115
	s_waitcnt lgkmcnt(0)
	v_max3_f32 v120, v192, v115, v117
	v_sub_f32_e32 v115, v192, v120
	v_exp_f32_e32 v124, v115
	v_mov_b64_e32 v[192:193], v[120:121]
	v_mul_f32_e32 v190, v190, v124
	v_pk_mul_f32 v[86:87], v[86:87], v[124:125] op_sel_hi:[1,0]
	v_pk_mul_f32 v[84:85], v[84:85], v[124:125] op_sel_hi:[1,0]
	v_pk_mul_f32 v[82:83], v[82:83], v[124:125] op_sel_hi:[1,0]
	v_pk_mul_f32 v[80:81], v[80:81], v[124:125] op_sel_hi:[1,0]
	v_pk_mul_f32 v[78:79], v[78:79], v[124:125] op_sel_hi:[1,0]
	v_pk_mul_f32 v[76:77], v[76:77], v[124:125] op_sel_hi:[1,0]
	v_pk_mul_f32 v[74:75], v[74:75], v[124:125] op_sel_hi:[1,0]
	v_pk_mul_f32 v[72:73], v[72:73], v[124:125] op_sel_hi:[1,0]
	s_branch .LBB0_370

; template <int MODE>
; __device__ __forceinline__ void nsa_compute(int cur, int buf, int t, int hl, u64 mymask, const bf16x8 (&Qf)[2][2], f32x4 (&O)[4][2], float (&m)[2], float (&l)[2],
;                                             const float (&inv)[2], float* impw, char* lds) {
;     ...
;         const float mxa = fmaxf(fmaxf(sv[0][0], sv[0][1]), sv[0][2]), mxb = fmaxf(fmaxf(sv[0][3], sv[1][0]), sv[1][1]);
;         float mx = fmaxf(fmaxf(fmaxf(sv[1][2], sv[1][3]), mxa), mxb);
;         if (MODE == 2) mx = selok ? mx : -__builtin_inff();
;         if (__any(mx > m[r] + 8.0f)) {
;           mx = fmaxf(mx, __shfl_xor(mx, 16)); mx = fmaxf(mx, __shfl_xor(mx, 32));
;           const float mn = fmaxf(m[r], mx), al = __builtin_amdgcn_exp2f(m[r] - mn);
;           m[r] = mn; l[r] *= al;
;           if (MODE != 0) {
; #pragma unroll
;             for (int df = 0; df < 4; ++df) O[df][r] *= al;
;           }
;         }
;         const float me = (MODE == 2) ? (selok ? m[r] : __builtin_inff()) : m[r];
;         float ps = 0.f;
; #pragma unroll
;         for (int kk = 0; kk < 2; ++kk)
; #pragma unroll
;           for (int e = 0; e < 4; ++e) { pv[kk][e] = __builtin_amdgcn_exp2f(sv[kk][e] - me); ps += pv[kk][e]; }
;         l[r] += ps;
.LBB0_370:
	v_sub_f32_e32 v115, v123, v120
	v_exp_f32_e32 v115, v115
	v_sub_f32_e32 v117, v118, v120
	v_exp_f32_e32 v117, v117
	v_sub_f32_e32 v118, v122, v120
	v_exp_f32_e32 v118, v118
	v_sub_f32_e32 v116, v116, v120
	v_exp_f32_e32 v116, v116
	v_sub_f32_e32 v119, v119, v120
	v_exp_f32_e32 v119, v119
	v_sub_f32_e32 v114, v114, v120
	v_add_f32_e32 v121, v117, v115
	v_exp_f32_e32 v114, v114
	v_add_f32_e32 v121, v118, v121
	v_add_f32_e32 v121, v116, v121
	v_add_f32_e32 v121, v119, v121
	v_sub_f32_e32 v113, v113, v120
	v_add_f32_e32 v122, v114, v121
	v_exp_f32_e32 v121, v113
	v_sub_f32_e32 v112, v112, v120
	v_exp_f32_e32 v120, v112
	v_add_f32_e32 v113, v121, v122
	v_add_f32_e32 v112, v120, v113
	v_add_f32_e32 v190, v190, v112
	s_waitcnt lgkmcnt(3)
	v_fmamk_f32 v113, v100, 0x3e38aa3b, v199
	v_fmamk_f32 v112, v101, 0x3e38aa3b, v198
	s_waitcnt lgkmcnt(2)
	v_fmamk_f32 v101, v102, 0x3e38aa3b, v201
	v_fmamk_f32 v100, v103, 0x3e38aa3b, v200
	s_waitcnt lgkmcnt(1)
	v_fmamk_f32 v103, v88, 0x3e38aa3b, v203
	v_fmamk_f32 v102, v89, 0x3e38aa3b, v202
	s_waitcnt lgkmcnt(0)
	v_fmamk_f32 v89, v90, 0x3e38aa3b, v205
	v_fmamk_f32 v88, v91, 0x3e38aa3b, v204
	v_max3_f32 v90, v113, v112, v101
	v_max3_f32 v91, v100, v103, v102
	v_max_f32_e32 v122, v89, v88
	v_max3_f32 v90, v122, v90, v91
	v_add_f32_e32 v91, 0x41000000, v193
	v_cmp_gt_f32_e32 vcc, v90, v91
	s_cbranch_vccz .LBB0_372
	ds_bpermute_b32 v91, v233, v90
	v_max_f32_e32 v90, v90, v90
	s_waitcnt lgkmcnt(0)
	v_max_f32_e32 v91, v91, v91
	v_max_f32_e32 v90, v90, v91
	ds_bpermute_b32 v91, v234, v90
	s_waitcnt lgkmcnt(0)
	v_max3_f32 v90, v193, v90, v91
	v_sub_f32_e32 v91, v193, v90
	v_exp_f32_e32 v122, v91
	v_mov_b32_e32 v193, v90
	v_mul_f32_e32 v191, v191, v122
	v_pk_mul_f32 v[98:99], v[98:99], v[122:123] op_sel_hi:[1,0]
	v_pk_mul_f32 v[96:97], v[96:97], v[122:123] op_sel_hi:[1,0]
	v_pk_mul_f32 v[94:95], v[94:95], v[122:123] op_sel_hi:[1,0]
	v_pk_mul_f32 v[92:93], v[92:93], v[122:123] op_sel_hi:[1,0]
	v_pk_mul_f32 v[110:111], v[110:111], v[122:123] op_sel_hi:[1,0]
	v_pk_mul_f32 v[108:109], v[108:109], v[122:123] op_sel_hi:[1,0]
	v_pk_mul_f32 v[106:107], v[106:107], v[122:123] op_sel_hi:[1,0]
	v_pk_mul_f32 v[104:105], v[104:105], v[122:123] op_sel_hi:[1,0]
	v_mov_b64_e32 v[194:195], v[190:191]
	s_branch .LBB0_373

; template <int MODE>
; __device__ __forceinline__ void nsa_compute(int cur, int buf, int t, int hl, u64 mymask, const bf16x8 (&Qf)[2][2], f32x4 (&O)[4][2], float (&m)[2], float (&l)[2],
;                                             const float (&inv)[2], float* impw, char* lds) {
;     ...
;     for (int r = 0; r < 2; ++r) {
;       float sv[2][4];
; #pragma unroll
;       for (int kk = 0; kk < 2; ++kk)
; #pragma unroll
;         for (int e = 0; e < 4; ++e) {
;           const int off = 32 * s2 + 16 * kk + e;
;           int idx;
;           if (MODE <= 1) { idx = base - 16 * off; idx = idx > 0 ? idx : 0; } else idx = base - off;
;           sv[kk][e] = S[kk][r][e] * (0.125f * LOG2E) + tb[r * TS + idx];
;         }
;       float pv[2][4];
;       if (MODE == 1) {
; #pragma unroll
;         for (int kk = 0; kk < 2; ++kk)
; #pragma unroll
;           for (int e = 0; e < 4; ++e) pv[kk][e] = __builtin_amdgcn_exp2f(sv[kk][e] - m[r]) * inv[r];
; #pragma unroll
;         for (int kk = 0; kk < 2; ++kk) { g1s[kk] += pv[kk][0] + pv[kk][1] + pv[kk][2] + 0.5f * pv[kk][3]; p3s[kk] += 0.5f * pv[kk][3]; }
;       } else {
;         const float mxa = fmaxf(fmaxf(sv[0][0], sv[0][1]), sv[0][2]), mxb = fmaxf(fmaxf(sv[0][3], sv[1][0]), sv[1][1]);
;         float mx = fmaxf(fmaxf(fmaxf(sv[1][2], sv[1][3]), mxa), mxb);
;         if (MODE == 2) mx = selok ? mx : -__builtin_inff();
;         if (__any(mx > m[r] + 8.0f)) {
;           mx = fmaxf(mx, __shfl_xor(mx, 16)); mx = fmaxf(mx, __shfl_xor(mx, 32));
;           const float mn = fmaxf(m[r], mx), al = __builtin_amdgcn_exp2f(m[r] - mn);
;           m[r] = mn; l[r] *= al;
;           if (MODE != 0) {
; #pragma unroll
;             for (int df = 0; df < 4; ++df) O[df][r] *= al;
;           }
;         }
;         const float me = (MODE == 2) ? (selok ? m[r] : __builtin_inff()) : m[r];
;         float ps = 0.f;
; #pragma unroll
;         for (int kk = 0; kk < 2; ++kk)
; #pragma unroll
;           for (int e = 0; e < 4; ++e) { pv[kk][e] = __builtin_amdgcn_exp2f(sv[kk][e] - me); ps += pv[kk][e]; }
;         l[r] += ps;
;       }
;       if (MODE != 0) {
;         const unsigned w0 = pk2(pv[0][0], pv[0][1]), w1 = pk2(pv[0][2], pv[0][3]), w2 = pk2(pv[1][0], pv[1][1]), w3 = pk2(pv[1][2], pv[1][3]);
;         u32x4 pw; pw.x = w0; pw.y = w1; pw.z = w2; pw.w = w3;
;         Pf[r] = __builtin_bit_cast(bf16x8, pw);
;       }
;     }
.LBB0_385:
	v_sub_f32_e32 v119, v135, v118
	v_exp_f32_e32 v119, v119
	v_sub_f32_e32 v134, v134, v118
	v_exp_f32_e32 v134, v134
	v_sub_f32_e32 v145, v145, v118
	v_exp_f32_e32 v145, v145
	v_sub_f32_e32 v144, v144, v118
	v_exp_f32_e32 v144, v144
	v_sub_f32_e32 v133, v133, v118
	v_exp_f32_e32 v133, v133
	v_sub_f32_e32 v132, v132, v118
	v_add_f32_e32 v135, v134, v119
	v_exp_f32_e32 v132, v132
	v_sub_f32_e32 v117, v117, v118
	v_add_f32_e32 v135, v145, v135
	v_exp_f32_e32 v117, v117
	v_sub_f32_e32 v116, v116, v118
	v_add_f32_e32 v135, v144, v135
	v_exp_f32_e32 v116, v116
	v_add_f32_e32 v135, v133, v135
	v_add_f32_e32 v135, v132, v135
	v_add_f32_e32 v135, v117, v135
	s_lshl_b32 s16, s46, 9
	v_add_f32_e32 v118, v116, v135
	v_cvt_pk_bf16_f32 v167, v117, v116
	v_mul_u32_u24_e32 v116, 0x44, v149
	s_add_i32 s72, s71, s16
	v_lshlrev_b32_e32 v116, 1, v116
	v_lshlrev_b32_e32 v117, 1, v150
	v_add3_u32 v116, s72, v116, v117
	v_cvt_pk_bf16_f32 v161, v153, v155
	v_cvt_pk_bf16_f32 v162, v156, v157
	v_add_u32_e32 v155, 0x4000, v116
	v_add_u32_e32 v156, 0x4800, v116
	v_cvt_pk_bf16_f32 v160, v151, v152
	v_cvt_pk_bf16_f32 v163, v158, v159
	v_cvt_pk_bf16_f32 v164, v119, v134
	v_cvt_pk_bf16_f32 v166, v133, v132
	ds_read2_b64 v[132:135], v155 offset1:4
	ds_read2_b64 v[150:153], v156 offset0:16 offset1:20
	v_add_u32_e32 v157, 0x5000, v116
	v_add_u32_e32 v158, 0x5800, v116
	ds_read2_b64 v[168:171], v157 offset0:32 offset1:36
	ds_read2_b64 v[172:175], v158 offset0:48 offset1:52
	v_add_f32_e32 v197, v197, v118
	v_cvt_pk_bf16_f32 v165, v145, v144
	s_setprio 1
	s_waitcnt lgkmcnt(3)
	v_mfma_f32_16x16x32_bf16 v[116:119], v[132:135], v[160:163], v[112:115]
	v_mfma_f32_16x16x32_bf16 v[132:135], v[132:135], v[164:167], v[124:127]
	s_waitcnt lgkmcnt(2)
	v_mfma_f32_16x16x32_bf16 v[112:115], v[150:153], v[160:163], v[104:107]
	v_mfma_f32_16x16x32_bf16 v[128:131], v[150:153], v[164:167], v[128:131]
	s_waitcnt lgkmcnt(1)
	v_mfma_f32_16x16x32_bf16 v[108:111], v[168:171], v[160:163], v[108:111]
	v_mfma_f32_16x16x32_bf16 v[124:127], v[168:171], v[164:167], v[136:139]
	s_waitcnt lgkmcnt(0)
	v_mfma_f32_16x16x32_bf16 v[104:107], v[172:175], v[160:163], v[120:123]
	v_mfma_f32_16x16x32_bf16 v[120:123], v[172:175], v[164:167], v[140:143]
	s_setprio 0
	s_nop 1
	v_add_u32_e32 v140, v147, v146
	v_add_u32_e32 v148, v148, v146
	ds_read_b128 v[136:139], v140 offset:4096
	ds_read_b128 v[140:143], v140 offset:6144
	ds_read_b128 v[144:147], v148 offset:4096
	ds_read_b128 v[148:151], v148 offset:6144
	v_add_u32_e32 v251, 0xa00, v154
	ds_read2_b32 v[202:203], v154 offset0:31 offset1:32
	ds_read2_b32 v[204:205], v154 offset0:29 offset1:30
	ds_read2_b32 v[206:207], v154 offset0:15 offset1:16
	ds_read2_b32 v[208:209], v154 offset0:13 offset1:14
	ds_read2_b32 v[210:211], v251 offset0:31 offset1:32
	ds_read2_b32 v[236:237], v251 offset0:29 offset1:30
	ds_read2_b32 v[238:239], v251 offset0:15 offset1:16
	ds_read2_b32 v[240:241], v251 offset0:13 offset1:14
	s_setprio 1
	s_waitcnt lgkmcnt(11)
	v_mfma_f32_16x16x32_bf16 v[160:163], v[136:139], v[0:3], 0
	v_mfma_f32_16x16x32_bf16 v[136:139], v[136:139], v[8:11], 0
	s_waitcnt lgkmcnt(10)
	v_mfma_f32_16x16x32_bf16 v[168:171], v[140:143], v[8:11], 0
	v_mfma_f32_16x16x32_bf16 v[164:167], v[140:143], v[0:3], 0
	s_waitcnt lgkmcnt(9)
	v_mfma_f32_16x16x32_bf16 v[160:163], v[144:147], v[4:7], v[160:163]
	v_mfma_f32_16x16x32_bf16 v[140:143], v[144:147], v[12:15], v[136:139]
	s_waitcnt lgkmcnt(8)
	v_mfma_f32_16x16x32_bf16 v[136:139], v[148:151], v[12:15], v[168:171]
	v_mfma_f32_16x16x32_bf16 v[164:167], v[148:151], v[4:7], v[164:167]
	s_setprio 0
	s_waitcnt lgkmcnt(7)
	s_nop 1
	v_fmamk_f32 v160, v160, 0x3e38aa3b, v203
	v_fmamk_f32 v150, v161, 0x3e38aa3b, v202
	s_waitcnt lgkmcnt(6)
	v_fmamk_f32 v159, v162, 0x3e38aa3b, v205
	v_fmamk_f32 v148, v163, 0x3e38aa3b, v204
	s_waitcnt lgkmcnt(5)
	v_fmamk_f32 v151, v164, 0x3e38aa3b, v207
	v_fmamk_f32 v146, v165, 0x3e38aa3b, v206
	s_waitcnt lgkmcnt(4)
	v_fmamk_f32 v145, v166, 0x3e38aa3b, v209
	v_fmamk_f32 v144, v167, 0x3e38aa3b, v208
	v_max3_f32 v147, v160, v150, v159
	v_max3_f32 v149, v148, v151, v146
	v_max_f32_e32 v152, v145, v144
	v_max3_f32 v147, v152, v147, v149
	v_add_f32_e32 v149, 0x41000000, v192
	v_cmp_gt_f32_e32 vcc, v147, v149
	s_cbranch_vccz .LBB0_387
	ds_bpermute_b32 v149, v233, v147
	v_max_f32_e32 v147, v147, v147
	v_mov_b32_e32 v153, v193
	s_waitcnt lgkmcnt(0)
	v_max_f32_e32 v149, v149, v149
	v_max_f32_e32 v147, v147, v149
	ds_bpermute_b32 v149, v234, v147
	s_waitcnt lgkmcnt(0)
	v_max3_f32 v152, v192, v147, v149
	v_sub_f32_e32 v147, v192, v152
	v_exp_f32_e32 v162, v147
	v_mov_b64_e32 v[192:193], v[152:153]
	v_mul_f32_e32 v196, v196, v162
	v_pk_mul_f32 v[118:119], v[118:119], v[162:163] op_sel_hi:[1,0]
	v_pk_mul_f32 v[116:117], v[116:117], v[162:163] op_sel_hi:[1,0]
	v_pk_mul_f32 v[114:115], v[114:115], v[162:163] op_sel_hi:[1,0]
	v_pk_mul_f32 v[112:113], v[112:113], v[162:163] op_sel_hi:[1,0]
	v_pk_mul_f32 v[110:111], v[110:111], v[162:163] op_sel_hi:[1,0]
	v_pk_mul_f32 v[108:109], v[108:109], v[162:163] op_sel_hi:[1,0]
	v_pk_mul_f32 v[106:107], v[106:107], v[162:163] op_sel_hi:[1,0]
	v_pk_mul_f32 v[104:105], v[104:105], v[162:163] op_sel_hi:[1,0]
	s_branch .LBB0_388

; template <int MODE>
; __device__ __forceinline__ void nsa_compute(int cur, int buf, int t, int hl, u64 mymask, const bf16x8 (&Qf)[2][2], f32x4 (&O)[4][2], float (&m)[2], float (&l)[2],
;                                             const float (&inv)[2], float* impw, char* lds) {
;     ...
;         const float mxa = fmaxf(fmaxf(sv[0][0], sv[0][1]), sv[0][2]), mxb = fmaxf(fmaxf(sv[0][3], sv[1][0]), sv[1][1]);
;         float mx = fmaxf(fmaxf(fmaxf(sv[1][2], sv[1][3]), mxa), mxb);
;         if (MODE == 2) mx = selok ? mx : -__builtin_inff();
;         if (__any(mx > m[r] + 8.0f)) {
;           mx = fmaxf(mx, __shfl_xor(mx, 16)); mx = fmaxf(mx, __shfl_xor(mx, 32));
;           const float mn = fmaxf(m[r], mx), al = __builtin_amdgcn_exp2f(m[r] - mn);
;           m[r] = mn; l[r] *= al;
;           if (MODE != 0) {
; #pragma unroll
;             for (int df = 0; df < 4; ++df) O[df][r] *= al;
;           }
;         }
;         const float me = (MODE == 2) ? (selok ? m[r] : __builtin_inff()) : m[r];
;         float ps = 0.f;
; #pragma unroll
;         for (int kk = 0; kk < 2; ++kk)
; #pragma unroll
;           for (int e = 0; e < 4; ++e) { pv[kk][e] = __builtin_amdgcn_exp2f(sv[kk][e] - me); ps += pv[kk][e]; }
;         l[r] += ps;
.LBB0_388:
	v_sub_f32_e32 v147, v160, v152
	v_exp_f32_e32 v147, v147
	v_sub_f32_e32 v149, v150, v152
	v_exp_f32_e32 v149, v149
	v_sub_f32_e32 v150, v159, v152
	v_exp_f32_e32 v150, v150
	v_sub_f32_e32 v148, v148, v152
	v_exp_f32_e32 v148, v148
	v_sub_f32_e32 v151, v151, v152
	v_exp_f32_e32 v151, v151
	v_sub_f32_e32 v146, v146, v152
	v_add_f32_e32 v153, v149, v147
	v_exp_f32_e32 v146, v146
	v_add_f32_e32 v153, v150, v153
	v_add_f32_e32 v153, v148, v153
	v_add_f32_e32 v153, v151, v153
	v_sub_f32_e32 v145, v145, v152
	v_add_f32_e32 v159, v146, v153
	v_exp_f32_e32 v153, v145
	v_sub_f32_e32 v144, v144, v152
	v_exp_f32_e32 v152, v144
	v_add_f32_e32 v145, v153, v159
	v_add_f32_e32 v144, v152, v145
	v_add_f32_e32 v196, v196, v144
	s_waitcnt lgkmcnt(3)
	v_fmamk_f32 v145, v140, 0x3e38aa3b, v211
	v_fmamk_f32 v144, v141, 0x3e38aa3b, v210
	s_waitcnt lgkmcnt(2)
	v_fmamk_f32 v141, v142, 0x3e38aa3b, v237
	v_fmamk_f32 v140, v143, 0x3e38aa3b, v236
	s_waitcnt lgkmcnt(1)
	v_fmamk_f32 v143, v136, 0x3e38aa3b, v239
	v_fmamk_f32 v142, v137, 0x3e38aa3b, v238
	s_waitcnt lgkmcnt(0)
	v_fmamk_f32 v137, v138, 0x3e38aa3b, v241
	v_fmamk_f32 v136, v139, 0x3e38aa3b, v240
	v_max3_f32 v138, v145, v144, v141
	v_max3_f32 v139, v140, v143, v142
	v_max_f32_e32 v154, v137, v136
	v_max3_f32 v138, v154, v138, v139
	v_add_f32_e32 v139, 0x41000000, v193
	v_cmp_gt_f32_e32 vcc, v138, v139
	s_cbranch_vccz .LBB0_390
	ds_bpermute_b32 v139, v233, v138
	v_max_f32_e32 v138, v138, v138
	s_waitcnt lgkmcnt(0)
	v_max_f32_e32 v139, v139, v139
	v_max_f32_e32 v138, v138, v139
	ds_bpermute_b32 v139, v234, v138
	s_waitcnt lgkmcnt(0)
	v_max3_f32 v138, v193, v138, v139
	v_sub_f32_e32 v139, v193, v138
	v_exp_f32_e32 v154, v139
	v_mov_b32_e32 v193, v138
	v_mul_f32_e32 v197, v197, v154
	v_pk_mul_f32 v[134:135], v[134:135], v[154:155] op_sel_hi:[1,0]
	v_pk_mul_f32 v[132:133], v[132:133], v[154:155] op_sel_hi:[1,0]
	v_pk_mul_f32 v[130:131], v[130:131], v[154:155] op_sel_hi:[1,0]
	v_pk_mul_f32 v[128:129], v[128:129], v[154:155] op_sel_hi:[1,0]
	v_pk_mul_f32 v[126:127], v[126:127], v[154:155] op_sel_hi:[1,0]
	v_pk_mul_f32 v[124:125], v[124:125], v[154:155] op_sel_hi:[1,0]
	v_pk_mul_f32 v[122:123], v[122:123], v[154:155] op_sel_hi:[1,0]
	v_pk_mul_f32 v[120:121], v[120:121], v[154:155] op_sel_hi:[1,0]
	s_branch .LBB0_391

; template <int MODE>
; __device__ __forceinline__ void nsa_compute(int cur, int buf, int t, int hl, u64 mymask, const bf16x8 (&Qf)[2][2], f32x4 (&O)[4][2], float (&m)[2], float (&l)[2],
;                                             const float (&inv)[2], float* impw, char* lds) {
;     ...
;     for (int r = 0; r < 2; ++r) {
;       float sv[2][4];
; #pragma unroll
;       for (int kk = 0; kk < 2; ++kk)
; #pragma unroll
;         for (int e = 0; e < 4; ++e) {
;           const int off = 32 * s2 + 16 * kk + e;
;           int idx;
;           if (MODE <= 1) { idx = base - 16 * off; idx = idx > 0 ? idx : 0; } else idx = base - off;
;           sv[kk][e] = S[kk][r][e] * (0.125f * LOG2E) + tb[r * TS + idx];
;         }
;       float pv[2][4];
;       if (MODE == 1) {
; #pragma unroll
;         for (int kk = 0; kk < 2; ++kk)
; #pragma unroll
;           for (int e = 0; e < 4; ++e) pv[kk][e] = __builtin_amdgcn_exp2f(sv[kk][e] - m[r]) * inv[r];
; #pragma unroll
;         for (int kk = 0; kk < 2; ++kk) { g1s[kk] += pv[kk][0] + pv[kk][1] + pv[kk][2] + 0.5f * pv[kk][3]; p3s[kk] += 0.5f * pv[kk][3]; }
;       } else {
;         const float mxa = fmaxf(fmaxf(sv[0][0], sv[0][1]), sv[0][2]), mxb = fmaxf(fmaxf(sv[0][3], sv[1][0]), sv[1][1]);
;         float mx = fmaxf(fmaxf(fmaxf(sv[1][2], sv[1][3]), mxa), mxb);
;         if (MODE == 2) mx = selok ? mx : -__builtin_inff();
;         if (__any(mx > m[r] + 8.0f)) {
;           mx = fmaxf(mx, __shfl_xor(mx, 16)); mx = fmaxf(mx, __shfl_xor(mx, 32));
;           const float mn = fmaxf(m[r], mx), al = __builtin_amdgcn_exp2f(m[r] - mn);
;           m[r] = mn; l[r] *= al;
;           if (MODE != 0) {
; #pragma unroll
;             for (int df = 0; df < 4; ++df) O[df][r] *= al;
;           }
;         }
;         const float me = (MODE == 2) ? (selok ? m[r] : __builtin_inff()) : m[r];
;         float ps = 0.f;
; #pragma unroll
;         for (int kk = 0; kk < 2; ++kk)
; #pragma unroll
;           for (int e = 0; e < 4; ++e) { pv[kk][e] = __builtin_amdgcn_exp2f(sv[kk][e] - me); ps += pv[kk][e]; }
;         l[r] += ps;
;       }
;       if (MODE != 0) {
;         const unsigned w0 = pk2(pv[0][0], pv[0][1]), w1 = pk2(pv[0][2], pv[0][3]), w2 = pk2(pv[1][0], pv[1][1]), w3 = pk2(pv[1][2], pv[1][3]);
;         u32x4 pw; pw.x = w0; pw.y = w1; pw.z = w2; pw.w = w3;
;         Pf[r] = __builtin_bit_cast(bf16x8, pw);
;       }
;     }
.LBB0_402:
	v_sub_f32_e32 v173, v173, v238
	v_exp_f32_e32 v173, v173
	v_sub_f32_e32 v172, v172, v238
	v_exp_f32_e32 v172, v172
	v_sub_f32_e32 v175, v175, v238
	v_exp_f32_e32 v175, v175
	v_sub_f32_e32 v174, v174, v238
	v_exp_f32_e32 v174, v174
	v_sub_f32_e32 v125, v125, v238
	v_cvt_pk_bf16_f32 v202, v202, v203
	v_cvt_pk_bf16_f32 v203, v204, v205
	v_cvt_pk_bf16_f32 v204, v206, v207
	v_exp_f32_e32 v125, v125
	v_sub_f32_e32 v124, v124, v238
	v_add_f32_e32 v206, v172, v173
	v_exp_f32_e32 v124, v124
	v_add_f32_e32 v206, v175, v206
	v_add_f32_e32 v206, v174, v206
	v_sub_f32_e32 v127, v127, v238
	v_add_f32_e32 v206, v125, v206
	v_exp_f32_e32 v127, v127
	v_sub_f32_e32 v126, v126, v238
	v_add_f32_e32 v206, v124, v206
	v_exp_f32_e32 v126, v126
	v_cvt_pk_bf16_f32 v172, v173, v172
	v_cvt_pk_bf16_f32 v173, v175, v174
	v_cvt_pk_bf16_f32 v174, v125, v124
	v_mul_u32_u24_e32 v124, 0x44, v200
	v_lshlrev_b32_e32 v124, 1, v124
	v_lshlrev_b32_e32 v125, 1, v201
	v_add3_u32 v200, s43, v124, v125
	v_cvt_pk_bf16_f32 v205, v236, v237
	v_add_f32_e32 v206, v127, v206
	v_add_u32_e32 v236, 0x4000, v200
	v_add_u32_e32 v237, 0x4800, v200
	v_add_f32_e32 v206, v126, v206
	v_cvt_pk_bf16_f32 v175, v127, v126
	ds_read2_b64 v[124:127], v236 offset1:4
	ds_read2_b64 v[240:243], v237 offset0:16 offset1:20
	v_add_u32_e32 v238, 0x5000, v200
	v_add_u32_e32 v239, 0x5800, v200
	ds_read2_b64 v[244:247], v238 offset0:32 offset1:36
	ds_read2_b64 v[248:251], v239 offset0:48 offset1:52
	v_add_f32_e32 v191, v191, v206
	s_setprio 1
	s_waitcnt lgkmcnt(3)
	v_mfma_f32_16x16x32_bf16 v[104:107], v[124:127], v[202:205], v[104:107]
	v_mfma_f32_16x16x32_bf16 v[124:127], v[124:127], v[172:175], v[120:123]
	s_waitcnt lgkmcnt(2)
	v_mfma_f32_16x16x32_bf16 v[108:111], v[240:243], v[202:205], v[108:111]
	v_mfma_f32_16x16x32_bf16 v[128:131], v[240:243], v[172:175], v[128:131]
	s_waitcnt lgkmcnt(1)
	v_mfma_f32_16x16x32_bf16 v[112:115], v[244:247], v[202:205], v[112:115]
	v_mfma_f32_16x16x32_bf16 v[132:135], v[244:247], v[172:175], v[132:135]
	s_waitcnt lgkmcnt(0)
	v_mfma_f32_16x16x32_bf16 v[120:123], v[248:251], v[202:205], v[116:119]
	v_mfma_f32_16x16x32_bf16 v[168:171], v[248:251], v[172:175], v[168:171]
	s_setprio 0
	s_nop 0
	ds_read_b128 v[116:119], v198 offset:4096
	ds_read_b128 v[172:175], v198 offset:6144
	ds_read_b128 v[200:203], v199 offset:4096
	ds_read_b128 v[204:207], v199 offset:6144
	s_setprio 1
	s_waitcnt lgkmcnt(3)
	v_mfma_f32_16x16x32_bf16 v[240:243], v[116:119], v[0:3], 0
	v_mfma_f32_16x16x32_bf16 v[116:119], v[116:119], v[8:11], 0
	s_waitcnt lgkmcnt(2)
	v_mfma_f32_16x16x32_bf16 v[248:251], v[172:175], v[8:11], 0
	v_mfma_f32_16x16x32_bf16 v[244:247], v[172:175], v[0:3], 0
	s_waitcnt lgkmcnt(1)
	v_mfma_f32_16x16x32_bf16 v[172:175], v[200:203], v[12:15], v[116:119]
	s_waitcnt lgkmcnt(0)
	v_mfma_f32_16x16x32_bf16 v[116:119], v[204:207], v[12:15], v[248:251]
	v_mfma_f32_16x16x32_bf16 v[208:211], v[200:203], v[4:7], v[240:243]
	v_mfma_f32_16x16x32_bf16 v[242:245], v[204:207], v[4:7], v[244:247]
	s_setprio 0
	ds_read2_b32 v[204:205], v176 offset0:31 offset1:32
	ds_read2_b32 v[202:203], v176 offset0:29 offset1:30
	ds_read2_b32 v[200:201], v176 offset0:15 offset1:16
	ds_read2_b32 v[198:199], v176 offset0:13 offset1:14
	s_waitcnt lgkmcnt(3)
	s_nop 0
	v_fmamk_f32 v241, v208, 0x3e38aa3b, v205
	v_fmac_f32_e32 v204, 0x3e38aa3b, v209
	s_waitcnt lgkmcnt(2)
	v_fmamk_f32 v240, v210, 0x3e38aa3b, v203
	v_fmac_f32_e32 v202, 0x3e38aa3b, v211
	s_waitcnt lgkmcnt(1)
	v_fmamk_f32 v205, v242, 0x3e38aa3b, v201
	v_fmac_f32_e32 v200, 0x3e38aa3b, v243
	s_waitcnt lgkmcnt(0)
	v_fmamk_f32 v199, v244, 0x3e38aa3b, v199
	v_fmac_f32_e32 v198, 0x3e38aa3b, v245
	v_max3_f32 v201, v241, v204, v240
	v_max3_f32 v203, v202, v205, v200
	v_max_f32_e32 v206, v199, v198
	v_max3_f32 v201, v206, v201, v203
	v_add_f32_e32 v203, 0x41000000, v192
	v_cmp_gt_f32_e32 vcc, v201, v203
	s_cbranch_vccz .LBB0_404
	ds_bpermute_b32 v203, v233, v201
	v_max_f32_e32 v201, v201, v201
	v_mov_b32_e32 v207, v193
	s_waitcnt lgkmcnt(0)
	v_max_f32_e32 v203, v203, v203
	v_max_f32_e32 v201, v201, v203
	ds_bpermute_b32 v203, v234, v201
	s_waitcnt lgkmcnt(0)
	v_max3_f32 v206, v192, v201, v203
	v_sub_f32_e32 v192, v192, v206
	v_exp_f32_e32 v192, v192
	s_nop 0
	v_mul_f32_e32 v190, v190, v192
	v_pk_mul_f32 v[106:107], v[106:107], v[192:193] op_sel_hi:[1,0]
	v_pk_mul_f32 v[104:105], v[104:105], v[192:193] op_sel_hi:[1,0]
	v_pk_mul_f32 v[110:111], v[110:111], v[192:193] op_sel_hi:[1,0]
	v_pk_mul_f32 v[108:109], v[108:109], v[192:193] op_sel_hi:[1,0]
	v_pk_mul_f32 v[114:115], v[114:115], v[192:193] op_sel_hi:[1,0]
	v_pk_mul_f32 v[112:113], v[112:113], v[192:193] op_sel_hi:[1,0]
	v_pk_mul_f32 v[122:123], v[122:123], v[192:193] op_sel_hi:[1,0]
	v_pk_mul_f32 v[120:121], v[120:121], v[192:193] op_sel_hi:[1,0]
	v_mov_b64_e32 v[192:193], v[206:207]
	s_branch .LBB0_405

; template <int MODE>
; __device__ __forceinline__ void nsa_compute(int cur, int buf, int t, int hl, u64 mymask, const bf16x8 (&Qf)[2][2], f32x4 (&O)[4][2], float (&m)[2], float (&l)[2],
;                                             const float (&inv)[2], float* impw, char* lds) {
;     ...
;     for (int r = 0; r < 2; ++r) {
;       float sv[2][4];
; #pragma unroll
;       for (int kk = 0; kk < 2; ++kk)
; #pragma unroll
;         for (int e = 0; e < 4; ++e) {
;           const int off = 32 * s2 + 16 * kk + e;
;           int idx;
;           if (MODE <= 1) { idx = base - 16 * off; idx = idx > 0 ? idx : 0; } else idx = base - off;
;           sv[kk][e] = S[kk][r][e] * (0.125f * LOG2E) + tb[r * TS + idx];
;         }
;       float pv[2][4];
;       if (MODE == 1) {
; #pragma unroll
;         for (int kk = 0; kk < 2; ++kk)
; #pragma unroll
;           for (int e = 0; e < 4; ++e) pv[kk][e] = __builtin_amdgcn_exp2f(sv[kk][e] - m[r]) * inv[r];
; #pragma unroll
;         for (int kk = 0; kk < 2; ++kk) { g1s[kk] += pv[kk][0] + pv[kk][1] + pv[kk][2] + 0.5f * pv[kk][3]; p3s[kk] += 0.5f * pv[kk][3]; }
;       } else {
;         const float mxa = fmaxf(fmaxf(sv[0][0], sv[0][1]), sv[0][2]), mxb = fmaxf(fmaxf(sv[0][3], sv[1][0]), sv[1][1]);
;         float mx = fmaxf(fmaxf(fmaxf(sv[1][2], sv[1][3]), mxa), mxb);
;         if (MODE == 2) mx = selok ? mx : -__builtin_inff();
;         if (__any(mx > m[r] + 8.0f)) {
;           mx = fmaxf(mx, __shfl_xor(mx, 16)); mx = fmaxf(mx, __shfl_xor(mx, 32));
;           const float mn = fmaxf(m[r], mx), al = __builtin_amdgcn_exp2f(m[r] - mn);
;           m[r] = mn; l[r] *= al;
;           if (MODE != 0) {
; #pragma unroll
;             for (int df = 0; df < 4; ++df) O[df][r] *= al;
;           }
;         }
;         const float me = (MODE == 2) ? (selok ? m[r] : __builtin_inff()) : m[r];
;         float ps = 0.f;
; #pragma unroll
;         for (int kk = 0; kk < 2; ++kk)
; #pragma unroll
;           for (int e = 0; e < 4; ++e) { pv[kk][e] = __builtin_amdgcn_exp2f(sv[kk][e] - me); ps += pv[kk][e]; }
;         l[r] += ps;
.LBB0_405:
	v_sub_f32_e32 v201, v241, v206
	v_exp_f32_e32 v201, v201
	v_sub_f32_e32 v203, v204, v206
	v_exp_f32_e32 v203, v203
	v_sub_f32_e32 v204, v240, v206
	v_exp_f32_e32 v204, v204
	v_sub_f32_e32 v202, v202, v206
	v_exp_f32_e32 v202, v202
	v_sub_f32_e32 v205, v205, v206
	v_exp_f32_e32 v205, v205
	v_sub_f32_e32 v200, v200, v206
	v_add_f32_e32 v207, v203, v201
	v_exp_f32_e32 v200, v200
	v_add_f32_e32 v207, v204, v207
	v_add_f32_e32 v207, v202, v207
	v_add_f32_e32 v207, v205, v207
	v_sub_f32_e32 v199, v199, v206
	v_add_f32_e32 v208, v200, v207
	v_exp_f32_e32 v207, v199
	v_sub_f32_e32 v198, v198, v206
	v_exp_f32_e32 v206, v198
	v_add_f32_e32 v199, v207, v208
	v_add_f32_e32 v198, v206, v199
	v_add_f32_e32 v190, v190, v198
	v_add_u32_e32 v198, 0xa7c, v176
	ds_read2_b32 v[198:199], v198 offset1:1
	s_waitcnt lgkmcnt(0)
	v_fmamk_f32 v199, v172, 0x3e38aa3b, v199
	v_add_u32_e32 v172, 0xa74, v176
	v_fmac_f32_e32 v198, 0x3e38aa3b, v173
	ds_read2_b32 v[172:173], v172 offset1:1
	s_waitcnt lgkmcnt(0)
	v_fmamk_f32 v173, v174, 0x3e38aa3b, v173
	v_add_u32_e32 v174, 0xa3c, v176
	v_fmac_f32_e32 v172, 0x3e38aa3b, v175
	ds_read2_b32 v[174:175], v174 offset1:1
	s_waitcnt lgkmcnt(0)
	v_fmamk_f32 v240, v116, 0x3e38aa3b, v175
	v_add_u32_e32 v116, 0xa34, v176
	v_fmac_f32_e32 v174, 0x3e38aa3b, v117
	ds_read2_b32 v[116:117], v116 offset1:1
	s_waitcnt lgkmcnt(0)
	v_fmamk_f32 v117, v118, 0x3e38aa3b, v117
	v_fmac_f32_e32 v116, 0x3e38aa3b, v119
	v_max3_f32 v118, v199, v198, v173
	v_max3_f32 v119, v172, v240, v174
	v_max_f32_e32 v175, v117, v116
	v_max3_f32 v118, v175, v118, v119
	v_add_f32_e32 v119, 0x41000000, v193
	v_cmp_gt_f32_e32 vcc, v118, v119
	s_cbranch_vccz .LBB0_407
	ds_bpermute_b32 v119, v233, v118
	v_max_f32_e32 v118, v118, v118
	s_waitcnt lgkmcnt(0)
	v_max_f32_e32 v119, v119, v119
	v_max_f32_e32 v118, v118, v119
	ds_bpermute_b32 v119, v234, v118
	s_waitcnt lgkmcnt(0)
	v_max3_f32 v118, v193, v118, v119
	v_sub_f32_e32 v119, v193, v118
	v_exp_f32_e32 v176, v119
	v_mov_b32_e32 v193, v118
	v_mul_f32_e32 v191, v191, v176
	v_pk_mul_f32 v[126:127], v[126:127], v[176:177] op_sel_hi:[1,0]
	v_pk_mul_f32 v[124:125], v[124:125], v[176:177] op_sel_hi:[1,0]
	v_pk_mul_f32 v[130:131], v[130:131], v[176:177] op_sel_hi:[1,0]
	v_pk_mul_f32 v[128:129], v[128:129], v[176:177] op_sel_hi:[1,0]
	v_pk_mul_f32 v[134:135], v[134:135], v[176:177] op_sel_hi:[1,0]
	v_pk_mul_f32 v[132:133], v[132:133], v[176:177] op_sel_hi:[1,0]
	v_pk_mul_f32 v[170:171], v[170:171], v[176:177] op_sel_hi:[1,0]
	v_pk_mul_f32 v[168:169], v[168:169], v[176:177] op_sel_hi:[1,0]
	s_branch .LBB0_408

; template <int MODE>
; __device__ __forceinline__ void nsa_compute(int cur, int buf, int t, int hl, u64 mymask, const bf16x8 (&Qf)[2][2], f32x4 (&O)[4][2], float (&m)[2], float (&l)[2],
;                                             const float (&inv)[2], float* impw, char* lds) {
;     ...
;     for (int r = 0; r < 2; ++r) {
;       float sv[2][4];
; #pragma unroll
;       for (int kk = 0; kk < 2; ++kk)
; #pragma unroll
;         for (int e = 0; e < 4; ++e) {
;           const int off = 32 * s2 + 16 * kk + e;
;           int idx;
;           if (MODE <= 1) { idx = base - 16 * off; idx = idx > 0 ? idx : 0; } else idx = base - off;
;           sv[kk][e] = S[kk][r][e] * (0.125f * LOG2E) + tb[r * TS + idx];
;         }
;       float pv[2][4];
;       if (MODE == 1) {
; #pragma unroll
;         for (int kk = 0; kk < 2; ++kk)
; #pragma unroll
;           for (int e = 0; e < 4; ++e) pv[kk][e] = __builtin_amdgcn_exp2f(sv[kk][e] - m[r]) * inv[r];
; #pragma unroll
;         for (int kk = 0; kk < 2; ++kk) { g1s[kk] += pv[kk][0] + pv[kk][1] + pv[kk][2] + 0.5f * pv[kk][3]; p3s[kk] += 0.5f * pv[kk][3]; }
;       } else {
;         const float mxa = fmaxf(fmaxf(sv[0][0], sv[0][1]), sv[0][2]), mxb = fmaxf(fmaxf(sv[0][3], sv[1][0]), sv[1][1]);
;         float mx = fmaxf(fmaxf(fmaxf(sv[1][2], sv[1][3]), mxa), mxb);
;         if (MODE == 2) mx = selok ? mx : -__builtin_inff();
;         if (__any(mx > m[r] + 8.0f)) {
;           mx = fmaxf(mx, __shfl_xor(mx, 16)); mx = fmaxf(mx, __shfl_xor(mx, 32));
;           const float mn = fmaxf(m[r], mx), al = __builtin_amdgcn_exp2f(m[r] - mn);
;           m[r] = mn; l[r] *= al;
;           if (MODE != 0) {
; #pragma unroll
;             for (int df = 0; df < 4; ++df) O[df][r] *= al;
;           }
;         }
;         const float me = (MODE == 2) ? (selok ? m[r] : __builtin_inff()) : m[r];
;         float ps = 0.f;
; #pragma unroll
;         for (int kk = 0; kk < 2; ++kk)
; #pragma unroll
;           for (int e = 0; e < 4; ++e) { pv[kk][e] = __builtin_amdgcn_exp2f(sv[kk][e] - me); ps += pv[kk][e]; }
;         l[r] += ps;
;       }
;       if (MODE != 0) {
;         const unsigned w0 = pk2(pv[0][0], pv[0][1]), w1 = pk2(pv[0][2], pv[0][3]), w2 = pk2(pv[1][0], pv[1][1]), w3 = pk2(pv[1][2], pv[1][3]);
;         u32x4 pw; pw.x = w0; pw.y = w1; pw.z = w2; pw.w = w3;
;         Pf[r] = __builtin_bit_cast(bf16x8, pw);
;       }
;     }
.LBB0_442:
	v_cndmask_b32_e64 v74, v74, v228, s[36:37]
	v_sub_f32_e32 v75, v81, v74
	v_exp_f32_e32 v75, v75
	v_sub_f32_e32 v80, v80, v74
	v_exp_f32_e32 v80, v80
	v_sub_f32_e32 v78, v78, v74
	v_exp_f32_e32 v78, v78
	v_sub_f32_e32 v81, v82, v74
	v_exp_f32_e32 v81, v81
	v_sub_f32_e32 v77, v77, v74
	v_exp_f32_e32 v77, v77
	v_sub_f32_e32 v76, v76, v74
	v_add_f32_e32 v79, v80, v75
	v_exp_f32_e32 v76, v76
	v_sub_f32_e32 v73, v73, v74
	v_add_f32_e32 v79, v78, v79
	v_exp_f32_e32 v73, v73
	v_sub_f32_e32 v72, v72, v74
	v_add_f32_e32 v79, v81, v79
	v_exp_f32_e32 v72, v72
	v_add_f32_e32 v79, v77, v79
	v_add_f32_e32 v79, v76, v79
	v_add_f32_e32 v79, v73, v79
	s_lshl_b32 s17, s74, 9
	v_add_f32_e32 v74, v72, v79
	v_cvt_pk_bf16_f32 v101, v73, v72
	v_mul_u32_u24_e32 v72, 0x44, v94
	s_add_i32 s71, s63, s17
	v_lshlrev_b32_e32 v72, 1, v72
	v_lshlrev_b32_e32 v73, 1, v95
	v_add3_u32 v72, s71, v72, v73
	v_add_u32_e32 v94, 0x4000, v72
	v_cvt_pk_bf16_f32 v87, v87, v88
	v_cvt_pk_bf16_f32 v88, v89, v96
	v_cvt_pk_bf16_f32 v89, v97, v84
	v_cvt_pk_bf16_f32 v99, v78, v81
	v_cvt_pk_bf16_f32 v100, v77, v76
	ds_read2_b64 v[76:79], v94 offset1:4
	v_add_u32_e32 v95, 0x4800, v72
	v_add_u32_e32 v96, 0x5000, v72
	v_add_u32_e32 v97, 0x5800, v72
	ds_read2_b64 v[102:105], v95 offset0:16 offset1:20
	ds_read2_b64 v[106:109], v96 offset0:32 offset1:36
	ds_read2_b64 v[110:113], v97 offset0:48 offset1:52
	v_cvt_pk_bf16_f32 v86, v85, v86
	v_add_f32_e32 v191, v191, v74
	v_cvt_pk_bf16_f32 v98, v75, v80
	s_setprio 1
	s_waitcnt lgkmcnt(3)
	v_mfma_f32_16x16x32_bf16 v[72:75], v[76:79], v[86:89], v[16:19]
	v_mfma_f32_16x16x32_bf16 v[80:83], v[76:79], v[98:101], v[20:23]
	s_waitcnt lgkmcnt(2)
	v_mfma_f32_16x16x32_bf16 v[24:27], v[102:105], v[86:89], v[24:27]
	v_mfma_f32_16x16x32_bf16 v[76:79], v[102:105], v[98:101], v[28:31]
	s_waitcnt lgkmcnt(1)
	v_mfma_f32_16x16x32_bf16 v[20:23], v[106:109], v[86:89], v[32:35]
	v_mfma_f32_16x16x32_bf16 v[32:35], v[106:109], v[98:101], v[36:39]
	s_waitcnt lgkmcnt(0)
	v_mfma_f32_16x16x32_bf16 v[16:19], v[110:113], v[86:89], v[40:43]
	v_mfma_f32_16x16x32_bf16 v[28:31], v[110:113], v[98:101], v[44:47]
	s_setprio 0
	s_nop 0
	v_add_u32_e32 v40, v92, v91
	v_add_u32_e32 v84, v93, v91
	ds_read_b128 v[36:39], v40 offset:4096
	ds_read_b128 v[40:43], v40 offset:6144
	ds_read_b128 v[44:47], v84 offset:4096
	ds_read_b128 v[84:87], v84 offset:6144
	v_add_u32_e32 v251, 0x8400, v90
	v_add_u32_e32 v250, 0xc500, v90
	ds_read2_b32 v[138:139], v251 offset0:31 offset1:32
	ds_read2_b32 v[140:141], v251 offset0:29 offset1:30
	ds_read2_b32 v[142:143], v251 offset0:15 offset1:16
	ds_read2_b32 v[148:149], v251 offset0:13 offset1:14
	ds_read2_b32 v[150:151], v250 offset0:31 offset1:32
	ds_read2_b32 v[152:153], v250 offset0:29 offset1:30
	ds_read2_b32 v[154:155], v250 offset0:15 offset1:16
	ds_read2_b32 v[156:157], v250 offset0:13 offset1:14
	s_setprio 1
	s_waitcnt lgkmcnt(11)
	v_mfma_f32_16x16x32_bf16 v[98:101], v[36:39], v[0:3], 0
	v_mfma_f32_16x16x32_bf16 v[36:39], v[36:39], v[8:11], 0
	s_waitcnt lgkmcnt(10)
	v_mfma_f32_16x16x32_bf16 v[106:109], v[40:43], v[8:11], 0
	v_mfma_f32_16x16x32_bf16 v[102:105], v[40:43], v[0:3], 0
	s_waitcnt lgkmcnt(9)
	v_mfma_f32_16x16x32_bf16 v[40:43], v[44:47], v[12:15], v[36:39]
	s_waitcnt lgkmcnt(8)
	v_mfma_f32_16x16x32_bf16 v[36:39], v[84:87], v[12:15], v[106:109]
	v_mfma_f32_16x16x32_bf16 v[98:101], v[44:47], v[4:7], v[98:101]
	v_mfma_f32_16x16x32_bf16 v[102:105], v[84:87], v[4:7], v[102:105]
	s_setprio 0
	s_waitcnt lgkmcnt(7)
	s_nop 4
	v_fmamk_f32 v91, v98, 0x3e38aa3b, v139
	v_fmamk_f32 v84, v99, 0x3e38aa3b, v138
	s_waitcnt lgkmcnt(6)
	v_fmamk_f32 v85, v100, 0x3e38aa3b, v141
	v_fmamk_f32 v46, v101, 0x3e38aa3b, v140
	s_waitcnt lgkmcnt(5)
	v_fmamk_f32 v45, v102, 0x3e38aa3b, v143
	v_fmamk_f32 v44, v103, 0x3e38aa3b, v142
	v_max3_f32 v47, v91, v84, v85
	s_waitcnt lgkmcnt(4)
	v_fmamk_f32 v92, v104, 0x3e38aa3b, v149
	v_fmamk_f32 v86, v105, 0x3e38aa3b, v148
	v_max3_f32 v87, v46, v45, v44
	v_max_f32_e32 v88, v92, v86
	v_max3_f32 v47, v88, v47, v87
	v_cndmask_b32_e64 v47, v47, v225, s[36:37]
	v_add_f32_e32 v87, 0x41000000, v188
	v_cmp_gt_f32_e32 vcc, v47, v87
	s_cbranch_vccz .LBB0_444
	ds_bpermute_b32 v87, v233, v47
	v_max_f32_e32 v47, v47, v47
	v_mov_b32_e32 v89, v189
	s_waitcnt lgkmcnt(0)
	v_max_f32_e32 v87, v87, v87
	v_max_f32_e32 v47, v47, v87
	ds_bpermute_b32 v87, v234, v47
	s_waitcnt lgkmcnt(0)
	v_max3_f32 v88, v188, v47, v87
	v_sub_f32_e32 v47, v188, v88
	v_exp_f32_e32 v98, v47
	v_mov_b64_e32 v[188:189], v[88:89]
	v_mul_f32_e32 v190, v190, v98
	v_pk_mul_f32 v[74:75], v[74:75], v[98:99] op_sel_hi:[1,0]
	v_pk_mul_f32 v[72:73], v[72:73], v[98:99] op_sel_hi:[1,0]
	v_pk_mul_f32 v[26:27], v[26:27], v[98:99] op_sel_hi:[1,0]
	v_pk_mul_f32 v[24:25], v[24:25], v[98:99] op_sel_hi:[1,0]
	v_pk_mul_f32 v[22:23], v[22:23], v[98:99] op_sel_hi:[1,0]
	v_pk_mul_f32 v[20:21], v[20:21], v[98:99] op_sel_hi:[1,0]
	v_pk_mul_f32 v[18:19], v[18:19], v[98:99] op_sel_hi:[1,0]
	v_pk_mul_f32 v[16:17], v[16:17], v[98:99] op_sel_hi:[1,0]
	s_branch .LBB0_445

; template <int MODE>
; __device__ __forceinline__ void nsa_compute(int cur, int buf, int t, int hl, u64 mymask, const bf16x8 (&Qf)[2][2], f32x4 (&O)[4][2], float (&m)[2], float (&l)[2],
;                                             const float (&inv)[2], float* impw, char* lds) {
;     ...
;         const float mxa = fmaxf(fmaxf(sv[0][0], sv[0][1]), sv[0][2]), mxb = fmaxf(fmaxf(sv[0][3], sv[1][0]), sv[1][1]);
;         float mx = fmaxf(fmaxf(fmaxf(sv[1][2], sv[1][3]), mxa), mxb);
;         if (MODE == 2) mx = selok ? mx : -__builtin_inff();
;         if (__any(mx > m[r] + 8.0f)) {
;           mx = fmaxf(mx, __shfl_xor(mx, 16)); mx = fmaxf(mx, __shfl_xor(mx, 32));
;           const float mn = fmaxf(m[r], mx), al = __builtin_amdgcn_exp2f(m[r] - mn);
;           m[r] = mn; l[r] *= al;
;           if (MODE != 0) {
; #pragma unroll
;             for (int df = 0; df < 4; ++df) O[df][r] *= al;
;           }
;         }
;         const float me = (MODE == 2) ? (selok ? m[r] : __builtin_inff()) : m[r];
;         float ps = 0.f;
; #pragma unroll
;         for (int kk = 0; kk < 2; ++kk)
; #pragma unroll
;           for (int e = 0; e < 4; ++e) { pv[kk][e] = __builtin_amdgcn_exp2f(sv[kk][e] - me); ps += pv[kk][e]; }
;         l[r] += ps;
.LBB0_445:
	v_cndmask_b32_e64 v93, v88, v228, s[36:37]
	v_sub_f32_e32 v47, v91, v93
	v_exp_f32_e32 v47, v47
	v_sub_f32_e32 v84, v84, v93
	v_exp_f32_e32 v84, v84
	v_sub_f32_e32 v85, v85, v93
	v_exp_f32_e32 v85, v85
	v_sub_f32_e32 v46, v46, v93
	v_exp_f32_e32 v46, v46
	v_add_f32_e32 v87, v84, v47
	v_add_f32_e32 v87, v85, v87
	v_sub_f32_e32 v45, v45, v93
	v_add_f32_e32 v88, v46, v87
	v_exp_f32_e32 v87, v45
	v_sub_f32_e32 v44, v44, v93
	v_add_f32_e32 v45, v87, v88
	v_exp_f32_e32 v88, v44
	s_nop 0
	v_add_f32_e32 v44, v88, v45
	v_sub_f32_e32 v45, v92, v93
	v_exp_f32_e32 v89, v45
	v_sub_f32_e32 v45, v86, v93
	v_exp_f32_e32 v86, v45
	v_add_f32_e32 v44, v89, v44
	v_add_f32_e32 v44, v86, v44
	v_add_f32_e32 v190, v190, v44
	s_waitcnt lgkmcnt(3)
	v_fmamk_f32 v45, v40, 0x3e38aa3b, v151
	v_fmamk_f32 v44, v41, 0x3e38aa3b, v150
	s_waitcnt lgkmcnt(2)
	v_fmamk_f32 v41, v42, 0x3e38aa3b, v153
	v_fmamk_f32 v40, v43, 0x3e38aa3b, v152
	s_waitcnt lgkmcnt(1)
	v_fmamk_f32 v43, v36, 0x3e38aa3b, v155
	v_fmamk_f32 v42, v37, 0x3e38aa3b, v154
	s_waitcnt lgkmcnt(0)
	v_fmamk_f32 v90, v38, 0x3e38aa3b, v157
	v_fmamk_f32 v36, v39, 0x3e38aa3b, v156
	v_max3_f32 v37, v45, v44, v41
	v_max3_f32 v38, v40, v43, v42
	v_max_f32_e32 v39, v90, v36
	v_max3_f32 v37, v39, v37, v38
	v_cndmask_b32_e64 v37, v37, v225, s[36:37]
	v_add_f32_e32 v38, 0x41000000, v189
	v_cmp_gt_f32_e32 vcc, v37, v38
	s_cbranch_vccz .LBB0_447
	ds_bpermute_b32 v38, v233, v37
	v_max_f32_e32 v37, v37, v37
	s_waitcnt lgkmcnt(0)
	v_max_f32_e32 v38, v38, v38
	v_max_f32_e32 v37, v37, v38
	ds_bpermute_b32 v38, v234, v37
	s_waitcnt lgkmcnt(0)
	v_max3_f32 v37, v189, v37, v38
	v_sub_f32_e32 v38, v189, v37
	v_exp_f32_e32 v38, v38
	v_mov_b32_e32 v189, v37
	v_mul_f32_e32 v191, v191, v38
	v_pk_mul_f32 v[82:83], v[82:83], v[38:39] op_sel_hi:[1,0]
	v_pk_mul_f32 v[80:81], v[80:81], v[38:39] op_sel_hi:[1,0]
	v_pk_mul_f32 v[78:79], v[78:79], v[38:39] op_sel_hi:[1,0]
	v_pk_mul_f32 v[76:77], v[76:77], v[38:39] op_sel_hi:[1,0]
	v_pk_mul_f32 v[34:35], v[34:35], v[38:39] op_sel_hi:[1,0]
	v_pk_mul_f32 v[32:33], v[32:33], v[38:39] op_sel_hi:[1,0]
	v_pk_mul_f32 v[30:31], v[30:31], v[38:39] op_sel_hi:[1,0]
	v_pk_mul_f32 v[28:29], v[28:29], v[38:39] op_sel_hi:[1,0]
	v_mov_b64_e32 v[144:145], v[190:191]
	s_branch .LBB0_448

; template <int MODE>
; __device__ __forceinline__ void nsa_compute(int cur, int buf, int t, int hl, u64 mymask, const bf16x8 (&Qf)[2][2], f32x4 (&O)[4][2], float (&m)[2], float (&l)[2],
;                                             const float (&inv)[2], float* impw, char* lds) {
;     ...
;     for (int r = 0; r < 2; ++r) {
;       float sv[2][4];
; #pragma unroll
;       for (int kk = 0; kk < 2; ++kk)
; #pragma unroll
;         for (int e = 0; e < 4; ++e) {
;           const int off = 32 * s2 + 16 * kk + e;
;           int idx;
;           if (MODE <= 1) { idx = base - 16 * off; idx = idx > 0 ? idx : 0; } else idx = base - off;
;           sv[kk][e] = S[kk][r][e] * (0.125f * LOG2E) + tb[r * TS + idx];
;         }
;       float pv[2][4];
;       if (MODE == 1) {
; #pragma unroll
;         for (int kk = 0; kk < 2; ++kk)
; #pragma unroll
;           for (int e = 0; e < 4; ++e) pv[kk][e] = __builtin_amdgcn_exp2f(sv[kk][e] - m[r]) * inv[r];
; #pragma unroll
;         for (int kk = 0; kk < 2; ++kk) { g1s[kk] += pv[kk][0] + pv[kk][1] + pv[kk][2] + 0.5f * pv[kk][3]; p3s[kk] += 0.5f * pv[kk][3]; }
;       } else {
;         const float mxa = fmaxf(fmaxf(sv[0][0], sv[0][1]), sv[0][2]), mxb = fmaxf(fmaxf(sv[0][3], sv[1][0]), sv[1][1]);
;         float mx = fmaxf(fmaxf(fmaxf(sv[1][2], sv[1][3]), mxa), mxb);
;         if (MODE == 2) mx = selok ? mx : -__builtin_inff();
;         if (__any(mx > m[r] + 8.0f)) {
;           mx = fmaxf(mx, __shfl_xor(mx, 16)); mx = fmaxf(mx, __shfl_xor(mx, 32));
;           const float mn = fmaxf(m[r], mx), al = __builtin_amdgcn_exp2f(m[r] - mn);
;           m[r] = mn; l[r] *= al;
;           if (MODE != 0) {
; #pragma unroll
;             for (int df = 0; df < 4; ++df) O[df][r] *= al;
;           }
;         }
;         const float me = (MODE == 2) ? (selok ? m[r] : __builtin_inff()) : m[r];
;         float ps = 0.f;
; #pragma unroll
;         for (int kk = 0; kk < 2; ++kk)
; #pragma unroll
;           for (int e = 0; e < 4; ++e) { pv[kk][e] = __builtin_amdgcn_exp2f(sv[kk][e] - me); ps += pv[kk][e]; }
;         l[r] += ps;
;       }
;       if (MODE != 0) {
;         const unsigned w0 = pk2(pv[0][0], pv[0][1]), w1 = pk2(pv[0][2], pv[0][3]), w2 = pk2(pv[1][0], pv[1][1]), w3 = pk2(pv[1][2], pv[1][3]);
;         u32x4 pw; pw.x = w0; pw.y = w1; pw.z = w2; pw.w = w3;
;         Pf[r] = __builtin_bit_cast(bf16x8, pw);
;       }
;     }
.LBB0_459:
	v_cndmask_b32_e64 v30, v30, v228, s[36:37]
	v_sub_f32_e32 v31, v47, v30
	v_exp_f32_e32 v31, v31
	v_sub_f32_e32 v46, v46, v30
	v_exp_f32_e32 v46, v46
	v_sub_f32_e32 v113, v113, v30
	v_exp_f32_e32 v113, v113
	v_sub_f32_e32 v112, v112, v30
	v_exp_f32_e32 v112, v112
	v_sub_f32_e32 v45, v45, v30
	v_exp_f32_e32 v45, v45
	v_sub_f32_e32 v44, v44, v30
	v_add_f32_e32 v47, v46, v31
	v_exp_f32_e32 v44, v44
	v_sub_f32_e32 v29, v29, v30
	v_add_f32_e32 v47, v113, v47
	v_exp_f32_e32 v29, v29
	v_sub_f32_e32 v28, v28, v30
	v_add_f32_e32 v47, v112, v47
	v_exp_f32_e32 v28, v28
	v_add_f32_e32 v47, v45, v47
	v_add_f32_e32 v47, v44, v47
	v_add_f32_e32 v47, v29, v47
	s_lshl_b32 s16, s74, 9
	v_add_f32_e32 v30, v28, v47
	v_cvt_pk_bf16_f32 v135, v29, v28
	v_mul_u32_u24_e32 v28, 0x44, v117
	s_add_i32 s73, s72, s16
	v_lshlrev_b32_e32 v28, 1, v28
	v_lshlrev_b32_e32 v29, 1, v118
	v_add3_u32 v28, s73, v28, v29
	v_cvt_pk_bf16_f32 v129, v121, v123
	v_cvt_pk_bf16_f32 v130, v124, v125
	v_add_u32_e32 v123, 0x4000, v28
	v_add_u32_e32 v124, 0x4800, v28
	v_cvt_pk_bf16_f32 v128, v119, v120
	v_cvt_pk_bf16_f32 v131, v126, v127
	v_cvt_pk_bf16_f32 v132, v31, v46
	v_cvt_pk_bf16_f32 v134, v45, v44
	ds_read2_b64 v[44:47], v123 offset1:4
	ds_read2_b64 v[118:121], v124 offset0:16 offset1:20
	v_add_u32_e32 v125, 0x5000, v28
	v_add_u32_e32 v126, 0x5800, v28
	ds_read2_b64 v[136:139], v125 offset0:32 offset1:36
	ds_read2_b64 v[140:143], v126 offset0:48 offset1:52
	v_add_f32_e32 v147, v147, v30
	v_cvt_pk_bf16_f32 v133, v113, v112
	s_setprio 1
	s_waitcnt lgkmcnt(3)
	v_mfma_f32_16x16x32_bf16 v[28:31], v[44:47], v[128:131], v[24:27]
	v_mfma_f32_16x16x32_bf16 v[44:47], v[44:47], v[132:135], v[36:39]
	s_waitcnt lgkmcnt(2)
	v_mfma_f32_16x16x32_bf16 v[24:27], v[118:121], v[128:131], v[16:19]
	v_mfma_f32_16x16x32_bf16 v[40:43], v[118:121], v[132:135], v[40:43]
	s_waitcnt lgkmcnt(1)
	v_mfma_f32_16x16x32_bf16 v[20:23], v[136:139], v[128:131], v[20:23]
	v_mfma_f32_16x16x32_bf16 v[36:39], v[136:139], v[132:135], v[104:107]
	s_waitcnt lgkmcnt(0)
	v_mfma_f32_16x16x32_bf16 v[16:19], v[140:143], v[128:131], v[32:35]
	v_mfma_f32_16x16x32_bf16 v[32:35], v[140:143], v[132:135], v[108:111]
	s_setprio 0
	s_nop 1
	v_add_u32_e32 v108, v115, v114
	v_add_u32_e32 v116, v116, v114
	ds_read_b128 v[104:107], v108 offset:4096
	ds_read_b128 v[108:111], v108 offset:6144
	ds_read_b128 v[112:115], v116 offset:4096
	ds_read_b128 v[116:119], v116 offset:6144
	v_add_u32_e32 v251, 0x8400, v122
	v_add_u32_e32 v250, 0xc500, v122
	ds_read2_b32 v[152:153], v251 offset0:31 offset1:32
	ds_read2_b32 v[154:155], v251 offset0:29 offset1:30
	ds_read2_b32 v[156:157], v251 offset0:15 offset1:16
	ds_read2_b32 v[168:169], v251 offset0:13 offset1:14
	ds_read2_b32 v[170:171], v250 offset0:31 offset1:32
	ds_read2_b32 v[172:173], v250 offset0:29 offset1:30
	ds_read2_b32 v[174:175], v250 offset0:15 offset1:16
	ds_read2_b32 v[192:193], v250 offset0:13 offset1:14
	s_setprio 1
	s_waitcnt lgkmcnt(11)
	v_mfma_f32_16x16x32_bf16 v[128:131], v[104:107], v[0:3], 0
	v_mfma_f32_16x16x32_bf16 v[104:107], v[104:107], v[8:11], 0
	s_waitcnt lgkmcnt(10)
	v_mfma_f32_16x16x32_bf16 v[136:139], v[108:111], v[8:11], 0
	v_mfma_f32_16x16x32_bf16 v[132:135], v[108:111], v[0:3], 0
	s_waitcnt lgkmcnt(9)
	v_mfma_f32_16x16x32_bf16 v[128:131], v[112:115], v[4:7], v[128:131]
	v_mfma_f32_16x16x32_bf16 v[108:111], v[112:115], v[12:15], v[104:107]
	s_waitcnt lgkmcnt(8)
	v_mfma_f32_16x16x32_bf16 v[104:107], v[116:119], v[12:15], v[136:139]
	v_mfma_f32_16x16x32_bf16 v[132:135], v[116:119], v[4:7], v[132:135]
	s_setprio 0
	s_waitcnt lgkmcnt(7)
	s_nop 1
	v_fmamk_f32 v127, v128, 0x3e38aa3b, v153
	v_fmamk_f32 v116, v129, 0x3e38aa3b, v152
	s_waitcnt lgkmcnt(6)
	v_fmamk_f32 v117, v130, 0x3e38aa3b, v155
	v_fmamk_f32 v114, v131, 0x3e38aa3b, v154
	s_waitcnt lgkmcnt(5)
	v_fmamk_f32 v113, v132, 0x3e38aa3b, v157
	v_fmamk_f32 v112, v133, 0x3e38aa3b, v156
	v_max3_f32 v115, v127, v116, v117
	s_waitcnt lgkmcnt(4)
	v_fmamk_f32 v128, v134, 0x3e38aa3b, v169
	v_fmamk_f32 v118, v135, 0x3e38aa3b, v168
	v_max3_f32 v119, v114, v113, v112
	v_max_f32_e32 v120, v128, v118
	v_max3_f32 v115, v120, v115, v119
	v_cndmask_b32_e64 v115, v115, v225, s[36:37]
	v_add_f32_e32 v119, 0x41000000, v188
	v_cmp_gt_f32_e32 vcc, v115, v119
	s_cbranch_vccz .LBB0_461
	ds_bpermute_b32 v119, v233, v115
	v_max_f32_e32 v115, v115, v115
	v_mov_b32_e32 v121, v189
	s_waitcnt lgkmcnt(0)
	v_max_f32_e32 v119, v119, v119
	v_max_f32_e32 v115, v115, v119
	ds_bpermute_b32 v119, v234, v115
	s_waitcnt lgkmcnt(0)
	v_max3_f32 v120, v188, v115, v119
	v_sub_f32_e32 v115, v188, v120
	v_exp_f32_e32 v130, v115
	v_mov_b64_e32 v[188:189], v[120:121]
	v_mul_f32_e32 v146, v146, v130
	v_pk_mul_f32 v[30:31], v[30:31], v[130:131] op_sel_hi:[1,0]
	v_pk_mul_f32 v[28:29], v[28:29], v[130:131] op_sel_hi:[1,0]
	v_pk_mul_f32 v[26:27], v[26:27], v[130:131] op_sel_hi:[1,0]
	v_pk_mul_f32 v[24:25], v[24:25], v[130:131] op_sel_hi:[1,0]
	v_pk_mul_f32 v[22:23], v[22:23], v[130:131] op_sel_hi:[1,0]
	v_pk_mul_f32 v[20:21], v[20:21], v[130:131] op_sel_hi:[1,0]
	v_pk_mul_f32 v[18:19], v[18:19], v[130:131] op_sel_hi:[1,0]
	v_pk_mul_f32 v[16:17], v[16:17], v[130:131] op_sel_hi:[1,0]
	s_branch .LBB0_462

; template <int MODE>
; __device__ __forceinline__ void nsa_compute(int cur, int buf, int t, int hl, u64 mymask, const bf16x8 (&Qf)[2][2], f32x4 (&O)[4][2], float (&m)[2], float (&l)[2],
;                                             const float (&inv)[2], float* impw, char* lds) {
;     ...
;         const float mxa = fmaxf(fmaxf(sv[0][0], sv[0][1]), sv[0][2]), mxb = fmaxf(fmaxf(sv[0][3], sv[1][0]), sv[1][1]);
;         float mx = fmaxf(fmaxf(fmaxf(sv[1][2], sv[1][3]), mxa), mxb);
;         if (MODE == 2) mx = selok ? mx : -__builtin_inff();
;         if (__any(mx > m[r] + 8.0f)) {
;           mx = fmaxf(mx, __shfl_xor(mx, 16)); mx = fmaxf(mx, __shfl_xor(mx, 32));
;           const float mn = fmaxf(m[r], mx), al = __builtin_amdgcn_exp2f(m[r] - mn);
;           m[r] = mn; l[r] *= al;
;           if (MODE != 0) {
; #pragma unroll
;             for (int df = 0; df < 4; ++df) O[df][r] *= al;
;           }
;         }
;         const float me = (MODE == 2) ? (selok ? m[r] : __builtin_inff()) : m[r];
;         float ps = 0.f;
; #pragma unroll
;         for (int kk = 0; kk < 2; ++kk)
; #pragma unroll
;           for (int e = 0; e < 4; ++e) { pv[kk][e] = __builtin_amdgcn_exp2f(sv[kk][e] - me); ps += pv[kk][e]; }
;         l[r] += ps;
.LBB0_462:
	v_cndmask_b32_e64 v129, v120, v228, s[36:37]
	v_sub_f32_e32 v115, v127, v129
	v_exp_f32_e32 v115, v115
	v_sub_f32_e32 v116, v116, v129
	v_exp_f32_e32 v116, v116
	v_sub_f32_e32 v117, v117, v129
	v_exp_f32_e32 v117, v117
	v_sub_f32_e32 v114, v114, v129
	v_exp_f32_e32 v114, v114
	v_add_f32_e32 v119, v116, v115
	v_add_f32_e32 v119, v117, v119
	v_sub_f32_e32 v113, v113, v129
	v_add_f32_e32 v120, v114, v119
	v_exp_f32_e32 v119, v113
	v_sub_f32_e32 v112, v112, v129
	v_add_f32_e32 v113, v119, v120
	v_exp_f32_e32 v120, v112
	s_nop 0
	v_add_f32_e32 v112, v120, v113
	v_sub_f32_e32 v113, v128, v129
	v_exp_f32_e32 v121, v113
	v_sub_f32_e32 v113, v118, v129
	v_exp_f32_e32 v118, v113
	v_add_f32_e32 v112, v121, v112
	v_add_f32_e32 v112, v118, v112
	v_add_f32_e32 v146, v146, v112
	s_waitcnt lgkmcnt(3)
	v_fmamk_f32 v113, v108, 0x3e38aa3b, v171
	v_fmamk_f32 v112, v109, 0x3e38aa3b, v170
	s_waitcnt lgkmcnt(2)
	v_fmamk_f32 v109, v110, 0x3e38aa3b, v173
	v_fmamk_f32 v108, v111, 0x3e38aa3b, v172
	s_waitcnt lgkmcnt(1)
	v_fmamk_f32 v111, v104, 0x3e38aa3b, v175
	v_fmamk_f32 v110, v105, 0x3e38aa3b, v174
	s_waitcnt lgkmcnt(0)
	v_fmamk_f32 v105, v106, 0x3e38aa3b, v193
	v_fmamk_f32 v104, v107, 0x3e38aa3b, v192
	v_max3_f32 v106, v113, v112, v109
	v_max3_f32 v107, v108, v111, v110
	v_max_f32_e32 v122, v105, v104
	v_max3_f32 v106, v122, v106, v107
	v_cndmask_b32_e64 v106, v106, v225, s[36:37]
	v_add_f32_e32 v107, 0x41000000, v189
	v_cmp_gt_f32_e32 vcc, v106, v107
	s_cbranch_vccz .LBB0_464
	ds_bpermute_b32 v107, v233, v106
	v_max_f32_e32 v106, v106, v106
	s_waitcnt lgkmcnt(0)
	v_max_f32_e32 v107, v107, v107
	v_max_f32_e32 v106, v106, v107
	ds_bpermute_b32 v107, v234, v106
	s_waitcnt lgkmcnt(0)
	v_max3_f32 v106, v189, v106, v107
	v_sub_f32_e32 v107, v189, v106
	v_exp_f32_e32 v122, v107
	v_mov_b32_e32 v189, v106
	v_mul_f32_e32 v147, v147, v122
	v_pk_mul_f32 v[46:47], v[46:47], v[122:123] op_sel_hi:[1,0]
	v_pk_mul_f32 v[44:45], v[44:45], v[122:123] op_sel_hi:[1,0]
	v_pk_mul_f32 v[42:43], v[42:43], v[122:123] op_sel_hi:[1,0]
	v_pk_mul_f32 v[40:41], v[40:41], v[122:123] op_sel_hi:[1,0]
	v_pk_mul_f32 v[38:39], v[38:39], v[122:123] op_sel_hi:[1,0]
	v_pk_mul_f32 v[36:37], v[36:37], v[122:123] op_sel_hi:[1,0]
	v_pk_mul_f32 v[34:35], v[34:35], v[122:123] op_sel_hi:[1,0]
	v_pk_mul_f32 v[32:33], v[32:33], v[122:123] op_sel_hi:[1,0]
	s_branch .LBB0_465

; template <int MODE>
; __device__ __forceinline__ void nsa_compute(int cur, int buf, int t, int hl, u64 mymask, const bf16x8 (&Qf)[2][2], f32x4 (&O)[4][2], float (&m)[2], float (&l)[2],
;                                             const float (&inv)[2], float* impw, char* lds) {
;     ...
;     for (int r = 0; r < 2; ++r) {
;       float sv[2][4];
; #pragma unroll
;       for (int kk = 0; kk < 2; ++kk)
; #pragma unroll
;         for (int e = 0; e < 4; ++e) {
;           const int off = 32 * s2 + 16 * kk + e;
;           int idx;
;           if (MODE <= 1) { idx = base - 16 * off; idx = idx > 0 ? idx : 0; } else idx = base - off;
;           sv[kk][e] = S[kk][r][e] * (0.125f * LOG2E) + tb[r * TS + idx];
;         }
;       float pv[2][4];
;       if (MODE == 1) {
; #pragma unroll
;         for (int kk = 0; kk < 2; ++kk)
; #pragma unroll
;           for (int e = 0; e < 4; ++e) pv[kk][e] = __builtin_amdgcn_exp2f(sv[kk][e] - m[r]) * inv[r];
; #pragma unroll
;         for (int kk = 0; kk < 2; ++kk) { g1s[kk] += pv[kk][0] + pv[kk][1] + pv[kk][2] + 0.5f * pv[kk][3]; p3s[kk] += 0.5f * pv[kk][3]; }
;       } else {
;         const float mxa = fmaxf(fmaxf(sv[0][0], sv[0][1]), sv[0][2]), mxb = fmaxf(fmaxf(sv[0][3], sv[1][0]), sv[1][1]);
;         float mx = fmaxf(fmaxf(fmaxf(sv[1][2], sv[1][3]), mxa), mxb);
;         if (MODE == 2) mx = selok ? mx : -__builtin_inff();
;         if (__any(mx > m[r] + 8.0f)) {
;           mx = fmaxf(mx, __shfl_xor(mx, 16)); mx = fmaxf(mx, __shfl_xor(mx, 32));
;           const float mn = fmaxf(m[r], mx), al = __builtin_amdgcn_exp2f(m[r] - mn);
;           m[r] = mn; l[r] *= al;
;           if (MODE != 0) {
; #pragma unroll
;             for (int df = 0; df < 4; ++df) O[df][r] *= al;
;           }
;         }
;         const float me = (MODE == 2) ? (selok ? m[r] : __builtin_inff()) : m[r];
;         float ps = 0.f;
; #pragma unroll
;         for (int kk = 0; kk < 2; ++kk)
; #pragma unroll
;           for (int e = 0; e < 4; ++e) { pv[kk][e] = __builtin_amdgcn_exp2f(sv[kk][e] - me); ps += pv[kk][e]; }
;         l[r] += ps;
;       }
;       if (MODE != 0) {
;         const unsigned w0 = pk2(pv[0][0], pv[0][1]), w1 = pk2(pv[0][2], pv[0][3]), w2 = pk2(pv[1][0], pv[1][1]), w3 = pk2(pv[1][2], pv[1][3]);
;         u32x4 pw; pw.x = w0; pw.y = w1; pw.z = w2; pw.w = w3;
;         Pf[r] = __builtin_bit_cast(bf16x8, pw);
;       }
;     }
.LBB0_476:
	v_cvt_pk_bf16_f32 v152, v152, v153
	v_cvt_pk_bf16_f32 v153, v154, v155
	v_cvt_pk_bf16_f32 v154, v156, v157
	v_cndmask_b32_e64 v156, v161, v228, s[36:37]
	v_sub_f32_e32 v139, v139, v156
	v_exp_f32_e32 v139, v139
	v_sub_f32_e32 v138, v138, v156
	v_exp_f32_e32 v138, v138
	v_sub_f32_e32 v141, v141, v156
	v_exp_f32_e32 v141, v141
	v_sub_f32_e32 v140, v140, v156
	v_exp_f32_e32 v140, v140
	v_sub_f32_e32 v137, v137, v156
	v_cvt_pk_bf16_f32 v155, v159, v160
	v_exp_f32_e32 v159, v137
	v_add_f32_e32 v157, v138, v139
	v_add_f32_e32 v157, v141, v157
	v_add_f32_e32 v157, v140, v157
	v_sub_f32_e32 v136, v136, v156
	v_add_f32_e32 v137, v159, v157
	v_exp_f32_e32 v157, v136
	s_nop 0
	v_add_f32_e32 v136, v157, v137
	v_sub_f32_e32 v137, v143, v156
	v_exp_f32_e32 v143, v137
	v_sub_f32_e32 v137, v142, v156
	v_exp_f32_e32 v142, v137
	v_cvt_pk_bf16_f32 v137, v141, v140
	v_mul_u32_u24_e32 v140, 0x44, v150
	v_add_f32_e32 v136, v143, v136
	v_lshlrev_b32_e32 v140, 1, v140
	v_lshlrev_b32_e32 v141, 1, v151
	v_add_f32_e32 v136, v142, v136
	v_add3_u32 v150, s71, v140, v141
	v_add_f32_e32 v191, v191, v136
	v_cvt_pk_bf16_f32 v136, v139, v138
	v_cvt_pk_bf16_f32 v138, v159, v157
	v_add_u32_e32 v159, 0x4000, v150
	v_add_u32_e32 v160, 0x4800, v150
	v_cvt_pk_bf16_f32 v139, v143, v142
	ds_read2_b64 v[140:143], v159 offset1:4
	ds_read2_b64 v[164:167], v160 offset0:16 offset1:20
	v_add_u32_e32 v161, 0x5000, v150
	v_add_u32_e32 v162, 0x5800, v150
	ds_read2_b64 v[168:171], v161 offset0:32 offset1:36
	ds_read2_b64 v[172:175], v162 offset0:48 offset1:52
	s_setprio 1
	s_waitcnt lgkmcnt(3)
	v_mfma_f32_16x16x32_bf16 v[16:19], v[140:143], v[152:155], v[16:19]
	v_mfma_f32_16x16x32_bf16 v[20:23], v[140:143], v[136:139], v[20:23]
	s_waitcnt lgkmcnt(2)
	v_mfma_f32_16x16x32_bf16 v[24:27], v[164:167], v[152:155], v[24:27]
	v_mfma_f32_16x16x32_bf16 v[28:31], v[164:167], v[136:139], v[28:31]
	s_waitcnt lgkmcnt(1)
	v_mfma_f32_16x16x32_bf16 v[32:35], v[168:171], v[152:155], v[32:35]
	v_mfma_f32_16x16x32_bf16 v[36:39], v[168:171], v[136:139], v[36:39]
	s_waitcnt lgkmcnt(0)
	v_mfma_f32_16x16x32_bf16 v[40:43], v[172:175], v[152:155], v[40:43]
	v_mfma_f32_16x16x32_bf16 v[44:47], v[172:175], v[136:139], v[44:47]
	s_setprio 0
	ds_read_b128 v[136:139], v148 offset:4096
	ds_read_b128 v[140:143], v148 offset:6144
	ds_read_b128 v[150:153], v149 offset:4096
	ds_read_b128 v[154:157], v149 offset:6144
	v_add_u32_e32 v251, 0x8400, v158
	v_add_u32_e32 v250, 0xc500, v158
	ds_read2_b32 v[192:193], v251 offset0:31 offset1:32
	ds_read2_b32 v[194:195], v251 offset0:29 offset1:30
	ds_read2_b32 v[198:199], v251 offset0:15 offset1:16
	ds_read2_b32 v[200:201], v251 offset0:13 offset1:14
	ds_read2_b32 v[202:203], v250 offset0:31 offset1:32
	ds_read2_b32 v[204:205], v250 offset0:29 offset1:30
	ds_read2_b32 v[206:207], v250 offset0:15 offset1:16
	ds_read2_b32 v[208:209], v250 offset0:13 offset1:14
	s_setprio 1
	s_waitcnt lgkmcnt(11)
	v_mfma_f32_16x16x32_bf16 v[164:167], v[136:139], v[0:3], 0
	v_mfma_f32_16x16x32_bf16 v[136:139], v[136:139], v[8:11], 0
	s_waitcnt lgkmcnt(10)
	v_mfma_f32_16x16x32_bf16 v[172:175], v[140:143], v[8:11], 0
	v_mfma_f32_16x16x32_bf16 v[168:171], v[140:143], v[0:3], 0
	s_waitcnt lgkmcnt(9)
	v_mfma_f32_16x16x32_bf16 v[164:167], v[150:153], v[4:7], v[164:167]
	v_mfma_f32_16x16x32_bf16 v[140:143], v[150:153], v[12:15], v[136:139]
	s_waitcnt lgkmcnt(8)
	v_mfma_f32_16x16x32_bf16 v[136:139], v[154:157], v[12:15], v[172:175]
	v_mfma_f32_16x16x32_bf16 v[168:171], v[154:157], v[4:7], v[168:171]
	s_setprio 0
	s_waitcnt lgkmcnt(7)
	s_nop 1
	v_fmamk_f32 v163, v164, 0x3e38aa3b, v193
	v_fmamk_f32 v152, v165, 0x3e38aa3b, v192
	s_waitcnt lgkmcnt(6)
	v_fmamk_f32 v153, v166, 0x3e38aa3b, v195
	v_fmamk_f32 v150, v167, 0x3e38aa3b, v194
	s_waitcnt lgkmcnt(5)
	v_fmamk_f32 v149, v168, 0x3e38aa3b, v199
	v_fmamk_f32 v148, v169, 0x3e38aa3b, v198
	v_max3_f32 v151, v163, v152, v153
	s_waitcnt lgkmcnt(4)
	v_fmamk_f32 v164, v170, 0x3e38aa3b, v201
	v_fmamk_f32 v154, v171, 0x3e38aa3b, v200
	v_max3_f32 v155, v150, v149, v148
	v_max_f32_e32 v156, v164, v154
	v_max3_f32 v151, v156, v151, v155
	v_cndmask_b32_e64 v151, v151, v225, s[36:37]
	v_add_f32_e32 v155, 0x41000000, v188
	v_cmp_gt_f32_e32 vcc, v151, v155
	s_cbranch_vccz .LBB0_478
	ds_bpermute_b32 v155, v233, v151
	v_max_f32_e32 v151, v151, v151
	v_mov_b32_e32 v157, v189
	s_waitcnt lgkmcnt(0)
	v_max_f32_e32 v155, v155, v155
	v_max_f32_e32 v151, v151, v155
	ds_bpermute_b32 v155, v234, v151
	s_waitcnt lgkmcnt(0)
	v_max3_f32 v156, v188, v151, v155
	v_sub_f32_e32 v151, v188, v156
	v_exp_f32_e32 v166, v151
	v_mov_b64_e32 v[188:189], v[156:157]
	v_mul_f32_e32 v190, v190, v166
	v_pk_mul_f32 v[18:19], v[18:19], v[166:167] op_sel_hi:[1,0]
	v_pk_mul_f32 v[16:17], v[16:17], v[166:167] op_sel_hi:[1,0]
	v_pk_mul_f32 v[26:27], v[26:27], v[166:167] op_sel_hi:[1,0]
	v_pk_mul_f32 v[24:25], v[24:25], v[166:167] op_sel_hi:[1,0]
	v_pk_mul_f32 v[34:35], v[34:35], v[166:167] op_sel_hi:[1,0]
	v_pk_mul_f32 v[32:33], v[32:33], v[166:167] op_sel_hi:[1,0]
	v_pk_mul_f32 v[42:43], v[42:43], v[166:167] op_sel_hi:[1,0]
	v_pk_mul_f32 v[40:41], v[40:41], v[166:167] op_sel_hi:[1,0]
	s_branch .LBB0_479

; template <int MODE>
; __device__ __forceinline__ void nsa_compute(int cur, int buf, int t, int hl, u64 mymask, const bf16x8 (&Qf)[2][2], f32x4 (&O)[4][2], float (&m)[2], float (&l)[2],
;                                             const float (&inv)[2], float* impw, char* lds) {
;     ...
;         const float mxa = fmaxf(fmaxf(sv[0][0], sv[0][1]), sv[0][2]), mxb = fmaxf(fmaxf(sv[0][3], sv[1][0]), sv[1][1]);
;         float mx = fmaxf(fmaxf(fmaxf(sv[1][2], sv[1][3]), mxa), mxb);
;         if (MODE == 2) mx = selok ? mx : -__builtin_inff();
;         if (__any(mx > m[r] + 8.0f)) {
;           mx = fmaxf(mx, __shfl_xor(mx, 16)); mx = fmaxf(mx, __shfl_xor(mx, 32));
;           const float mn = fmaxf(m[r], mx), al = __builtin_amdgcn_exp2f(m[r] - mn);
;           m[r] = mn; l[r] *= al;
;           if (MODE != 0) {
; #pragma unroll
;             for (int df = 0; df < 4; ++df) O[df][r] *= al;
;           }
;         }
;         const float me = (MODE == 2) ? (selok ? m[r] : __builtin_inff()) : m[r];
;         float ps = 0.f;
; #pragma unroll
;         for (int kk = 0; kk < 2; ++kk)
; #pragma unroll
;           for (int e = 0; e < 4; ++e) { pv[kk][e] = __builtin_amdgcn_exp2f(sv[kk][e] - me); ps += pv[kk][e]; }
;         l[r] += ps;
.LBB0_479:
	v_cndmask_b32_e64 v165, v156, v228, s[36:37]
	v_sub_f32_e32 v151, v163, v165
	v_exp_f32_e32 v151, v151
	v_sub_f32_e32 v152, v152, v165
	v_exp_f32_e32 v152, v152
	v_sub_f32_e32 v153, v153, v165
	v_exp_f32_e32 v153, v153
	v_sub_f32_e32 v150, v150, v165
	v_exp_f32_e32 v150, v150
	v_add_f32_e32 v155, v152, v151
	v_add_f32_e32 v155, v153, v155
	v_sub_f32_e32 v149, v149, v165
	v_add_f32_e32 v156, v150, v155
	v_exp_f32_e32 v155, v149
	v_sub_f32_e32 v148, v148, v165
	v_add_f32_e32 v149, v155, v156
	v_exp_f32_e32 v156, v148
	s_nop 0
	v_add_f32_e32 v148, v156, v149
	v_sub_f32_e32 v149, v164, v165
	v_exp_f32_e32 v157, v149
	v_sub_f32_e32 v149, v154, v165
	v_exp_f32_e32 v154, v149
	v_add_f32_e32 v148, v157, v148
	v_add_f32_e32 v148, v154, v148
	v_add_f32_e32 v190, v190, v148
	s_waitcnt lgkmcnt(3)
	v_fmamk_f32 v149, v140, 0x3e38aa3b, v203
	v_fmamk_f32 v148, v141, 0x3e38aa3b, v202
	s_waitcnt lgkmcnt(2)
	v_fmamk_f32 v141, v142, 0x3e38aa3b, v205
	v_fmamk_f32 v140, v143, 0x3e38aa3b, v204
	s_waitcnt lgkmcnt(1)
	v_fmamk_f32 v143, v136, 0x3e38aa3b, v207
	v_fmamk_f32 v142, v137, 0x3e38aa3b, v206
	s_waitcnt lgkmcnt(0)
	v_fmamk_f32 v158, v138, 0x3e38aa3b, v209
	v_fmamk_f32 v136, v139, 0x3e38aa3b, v208
	v_max3_f32 v137, v149, v148, v141
	v_max3_f32 v138, v140, v143, v142
	v_max_f32_e32 v139, v158, v136
	v_max3_f32 v137, v139, v137, v138
	v_cndmask_b32_e64 v137, v137, v225, s[36:37]
	v_add_f32_e32 v138, 0x41000000, v189
	v_cmp_gt_f32_e32 vcc, v137, v138
	s_cbranch_vccz .LBB0_481
	ds_bpermute_b32 v138, v233, v137
	v_max_f32_e32 v137, v137, v137
	s_waitcnt lgkmcnt(0)
	v_max_f32_e32 v138, v138, v138
	v_max_f32_e32 v137, v137, v138
	ds_bpermute_b32 v138, v234, v137
	s_waitcnt lgkmcnt(0)
	v_max3_f32 v137, v189, v137, v138
	v_sub_f32_e32 v138, v189, v137
	v_exp_f32_e32 v138, v138
	v_mov_b32_e32 v189, v137
	v_mul_f32_e32 v191, v191, v138
	v_pk_mul_f32 v[22:23], v[22:23], v[138:139] op_sel_hi:[1,0]
	v_pk_mul_f32 v[20:21], v[20:21], v[138:139] op_sel_hi:[1,0]
	v_pk_mul_f32 v[30:31], v[30:31], v[138:139] op_sel_hi:[1,0]
	v_pk_mul_f32 v[28:29], v[28:29], v[138:139] op_sel_hi:[1,0]
	v_pk_mul_f32 v[38:39], v[38:39], v[138:139] op_sel_hi:[1,0]
	v_pk_mul_f32 v[36:37], v[36:37], v[138:139] op_sel_hi:[1,0]
	v_pk_mul_f32 v[46:47], v[46:47], v[138:139] op_sel_hi:[1,0]
	v_pk_mul_f32 v[44:45], v[44:45], v[138:139] op_sel_hi:[1,0]
	s_branch .LBB0_482
